# v047 + nt on the 32 residual-tile loads of the out-proj/down residual epilogues
# baseline (speedup 1.0000x reference)
; #define PG8_LAS __attribute__((address_space(3)))
;     __device__ __forceinline__ void operator()(const f32x4 (&acc)[2][2][4][2], const Unit& u, int wr, int wc, int fr, int fq, PG8_LAS unsigned char* stg) const {
;         const int lane = fq * 16 + fr;
;         const size_t colw = (size_t)u.pn * BM + wc * 64;
;         const int rowb = u.pm * BM + wr * 64;
;         PG8_LAS unsigned char* st = stg + fr * 144 + fq * 16;
; #pragma unroll
;         for (int ai = 0; ai < 2; ++ai) {
;         asm volatile("" ::: "memory");
;         u32x4 xin[4][2];
; #pragma unroll
;         for (int m = 0; m < 4; ++m)
; #pragma unroll
;             for (int i = 0; i < 2; ++i) { const int c = lane + 64 * i; xin[m][i] = *(const u32x4*)(xb + (size_t)(rowb + ai * HALF + m * 16 + (c >> 3)) * 1024 + colw + (c & 7) * 8); }
; #pragma unroll
;         for (int m = 0; m < 4; ++m) {
;             const int row = rowb + ai * HALF + m * 16 + fr;
; #pragma unroll
;             for (int i = 0; i < 2; ++i) { const int c = lane + 64 * i; *(PG8_LAS u32x4*)(stg + (c >> 3) * 144 + (c & 7) * 16) = xin[m][i]; }
;             float ss = 0.f;
; #pragma unroll
;             for (int bj = 0; bj < 2; ++bj) {
;                 const u32x4 xo = *(const PG8_LAS u32x4*)(st + bj * 64);
;                 float v[8];
; #pragma unroll
;                 for (int i = 0; i < 4; ++i) { v[2 * i] = __uint_as_float(xo[i] << 16) + acc[ai][bj][m][i >> 1][(2 * i) & 3]; v[2 * i + 1] = __uint_as_float(xo[i] & 0xffff0000u) + acc[ai][bj][m][i >> 1][(2 * i + 1) & 3]; }
;                 u32x4 w; w.x = cvt_pk_bf16(v[0], v[1]); w.y = cvt_pk_bf16(v[2], v[3]); w.z = cvt_pk_bf16(v[4], v[5]); w.w = cvt_pk_bf16(v[6], v[7]);
;                 *(PG8_LAS u32x4*)(st + bj * 64) = w;
;                 ss += ((v[0] * v[0] + v[1] * v[1]) + (v[2] * v[2] + v[3] * v[3])) + ((v[4] * v[4] + v[5] * v[5]) + (v[6] * v[6] + v[7] * v[7]));
;             }
; #pragma unroll
;             for (int i = 0; i < 2; ++i) { const int c = lane + 64 * i; const u32x4 w = *(const PG8_LAS u32x4*)(stg + (c >> 3) * 144 + (c & 7) * 16);
;                 *(u32x4*)(xo_ + (size_t)(row - fr + (c >> 3)) * 1024 + colw + (c & 7) * 8) = w; }
;             ss = sum_x16(ss); ss = sum_x32(ss);
;             if (fq == 0) po_[(size_t)(u.pn * 4 + wc) * 65536 + row] = ss;
.LBB0_756:
	s_ashr_i32 s47, s46, 31
	s_lshl_b64 s[44:45], s[46:47], 8
	s_lshl_b32 s29, s50, 8
	s_or_b64 s[48:49], s[44:45], s[22:23]
	s_add_i32 s44, s29, s15
	v_or_b32_e32 v130, s44, v206
	s_lshl_b64 s[48:49], s[48:49], 1
	v_ashrrev_i32_e32 v131, 31, v130
	v_lshl_add_u64 v[182:183], v[176:177], 0, s[48:49]
	v_lshlrev_b64 v[198:199], 11, v[130:131]
	v_lshl_add_u64 v[130:131], v[182:183], 0, v[198:199]
	global_load_dwordx4 v[154:157], v[130:131], off nt
	v_or_b32_e32 v130, s44, v207
	v_ashrrev_i32_e32 v131, 31, v130
	v_lshlrev_b64 v[196:197], 11, v[130:131]
	v_lshl_add_u64 v[130:131], v[182:183], 0, v[196:197]
	global_load_dwordx4 v[160:163], v[130:131], off nt
	s_lshl_b32 s29, s46, 2
	s_or_b32 s46, s29, s13
	s_or_b32 s29, s44, 16
	v_or_b32_e32 v130, s29, v206
	v_ashrrev_i32_e32 v131, 31, v130
	v_lshlrev_b64 v[194:195], 11, v[130:131]
	v_lshl_add_u64 v[130:131], v[182:183], 0, v[194:195]
	global_load_dwordx4 v[146:149], v[130:131], off nt
	v_or_b32_e32 v130, s29, v207
	v_ashrrev_i32_e32 v131, 31, v130
	v_lshlrev_b64 v[192:193], 11, v[130:131]
	v_lshl_add_u64 v[130:131], v[182:183], 0, v[192:193]
	s_or_b32 s29, s44, 32
	global_load_dwordx4 v[150:153], v[130:131], off nt
	v_or_b32_e32 v130, s29, v206
	v_ashrrev_i32_e32 v131, 31, v130
	v_lshlrev_b64 v[188:189], 11, v[130:131]
	v_lshl_add_u64 v[130:131], v[182:183], 0, v[188:189]
	global_load_dwordx4 v[134:137], v[130:131], off nt
	v_or_b32_e32 v130, s29, v207
	v_ashrrev_i32_e32 v131, 31, v130
	v_lshlrev_b64 v[186:187], 11, v[130:131]
	v_lshl_add_u64 v[130:131], v[182:183], 0, v[186:187]
	s_or_b32 s29, s44, 48
	global_load_dwordx4 v[138:141], v[130:131], off nt
	v_or_b32_e32 v130, s29, v206
	v_or_b32_e32 v142, s29, v207
	v_ashrrev_i32_e32 v131, 31, v130
	v_ashrrev_i32_e32 v143, 31, v142
	v_lshlrev_b64 v[184:185], 11, v[130:131]
	v_lshlrev_b64 v[190:191], 11, v[142:143]
	v_lshl_add_u64 v[130:131], v[182:183], 0, v[184:185]
	v_lshl_add_u64 v[142:143], v[182:183], 0, v[190:191]
	global_load_dwordx4 v[130:133], v[130:131], off nt
	s_ashr_i32 s47, s46, 31
	global_load_dwordx4 v[142:145], v[142:143], off nt
	s_lshl_b64 s[46:47], s[46:47], 18
	s_waitcnt vmcnt(0)
	ds_write_b128 v209, v[154:157]
	ds_write_b128 v209, v[160:163] offset:1152
	ds_read_b128 v[154:157], v210
	s_waitcnt lgkmcnt(0)
	v_lshlrev_b32_e32 v160, 16, v154
	v_and_b32_e32 v154, 0xffff0000, v154
	v_add_f32_e32 v127, v127, v154
	v_lshlrev_b32_e32 v154, 16, v155
	v_add_f32_e32 v128, v128, v154
	v_and_b32_e32 v154, 0xffff0000, v155
	v_add_f32_e32 v129, v129, v154
	v_lshlrev_b32_e32 v154, 16, v156
	v_add_f32_e32 v154, v122, v154
	v_and_b32_e32 v122, 0xffff0000, v156
	v_add_f32_e32 v155, v123, v122
	v_lshlrev_b32_e32 v122, 16, v157
	v_add_f32_e32 v156, v124, v122
	v_and_b32_e32 v122, 0xffff0000, v157
	v_add_f32_e32 v126, v126, v160
	v_add_f32_e32 v157, v125, v122
	v_cvt_pk_bf16_f32 v122, v126, v127
	v_cvt_pk_bf16_f32 v123, v128, v129
	v_cvt_pk_bf16_f32 v124, v154, v155
	v_cvt_pk_bf16_f32 v125, v156, v157
	ds_write_b128 v210, v[122:125]
	v_mul_f32_e32 v122, v127, v127
	v_mul_f32_e32 v123, v129, v129
	v_fmac_f32_e32 v122, v126, v126
	v_fmac_f32_e32 v123, v128, v128
	v_add_f32_e32 v122, v122, v123
	v_mul_f32_e32 v123, v155, v155
	v_mul_f32_e32 v124, v157, v157
	v_fmac_f32_e32 v123, v154, v154
	v_fmac_f32_e32 v124, v156, v156
	v_add_f32_e32 v123, v123, v124
	v_add_f32_e32 v126, v122, v123
	ds_read_b128 v[122:125], v210 offset:64
	s_waitcnt lgkmcnt(0)
	v_lshlrev_b32_e32 v127, 16, v122
	v_and_b32_e32 v122, 0xffff0000, v122
	v_add_f32_e32 v119, v119, v122
	v_lshlrev_b32_e32 v122, 16, v123
	v_add_f32_e32 v120, v120, v122
	v_and_b32_e32 v122, 0xffff0000, v123
	v_add_f32_e32 v121, v121, v122
	v_lshlrev_b32_e32 v122, 16, v124
	v_add_f32_e32 v122, v114, v122
	v_and_b32_e32 v114, 0xffff0000, v124
	v_add_f32_e32 v123, v115, v114
	v_lshlrev_b32_e32 v114, 16, v125
	v_add_f32_e32 v124, v116, v114
	v_and_b32_e32 v114, 0xffff0000, v125
	v_add_f32_e32 v118, v118, v127
	v_add_f32_e32 v125, v117, v114
	v_cvt_pk_bf16_f32 v114, v118, v119
	v_cvt_pk_bf16_f32 v115, v120, v121
	v_cvt_pk_bf16_f32 v116, v122, v123
	v_cvt_pk_bf16_f32 v117, v124, v125
	ds_write_b128 v210, v[114:117] offset:64
	v_mul_f32_e32 v114, v119, v119
	v_mul_f32_e32 v115, v121, v121
	v_fmac_f32_e32 v114, v118, v118
	v_fmac_f32_e32 v115, v120, v120
	v_add_f32_e32 v114, v114, v115
	v_mul_f32_e32 v115, v123, v123
	v_mul_f32_e32 v116, v125, v125
	v_fmac_f32_e32 v115, v122, v122
	v_fmac_f32_e32 v116, v124, v124
	v_add_f32_e32 v115, v115, v116
	v_add_f32_e32 v114, v114, v115
	v_add_f32_e32 v120, v126, v114
	ds_read_b128 v[114:117], v211
	v_lshl_add_u64 v[118:119], s[76:77], 0, v[198:199]
	v_lshl_add_u64 v[118:119], v[118:119], 0, s[48:49]
	v_lshl_add_u64 v[118:119], v[118:119], 0, v[0:1]
	s_waitcnt lgkmcnt(0)
	global_store_dwordx4 v[118:119], v[114:117], off nt
	ds_read_b128 v[114:117], v211 offset:1152
	v_lshl_add_u64 v[118:119], s[76:77], 0, v[196:197]
	v_lshl_add_u64 v[118:119], v[118:119], 0, s[48:49]
	v_lshl_add_u64 v[118:119], v[118:119], 0, v[0:1]
	s_waitcnt lgkmcnt(0)
	global_store_dwordx4 v[118:119], v[114:117], off nt
	s_nop 1
	v_mov_b32_e32 v114, v120
	s_nop 1
	v_permlane16_swap_b32_e32 v120, v114
	v_add_f32_e32 v114, v120, v114
	v_mov_b32_e32 v115, v114
	s_nop 1
	v_permlane32_swap_b32_e32 v114, v115
	v_add_f32_e32 v164, v114, v115
	ds_write_b128 v209, v[146:149]
	ds_write_b128 v209, v[150:153] offset:1152
	ds_read_b128 v[114:117], v210
	s_waitcnt lgkmcnt(0)
; #define PG8_LAS __attribute__((address_space(3)))
; __device__ __forceinline__ unsigned cvt_pk_bf16(float lo, float hi) { unsigned r; asm volatile("v_cvt_pk_bf16_f32 %0, %1, %2" : "=v"(r) : "v"(lo), "v"(hi)); return r; }
; __device__ __forceinline__ float sum_x16(float s) { auto r = __builtin_amdgcn_permlane16_swap(__float_as_uint(s), __float_as_uint(s), false, false); return __uint_as_float(r[0]) + __uint_as_float(r[1]); }
; __device__ __forceinline__ float sum_x32(float s) { auto r = __builtin_amdgcn_permlane32_swap(__float_as_uint(s), __float_as_uint(s), false, false); return __uint_as_float(r[0]) + __uint_as_float(r[1]); }
;     __device__ __forceinline__ void operator()(const f32x4 (&acc)[2][2][4][2], const Unit& u, int wr, int wc, int fr, int fq, PG8_LAS unsigned char* stg) const {
;     ...
;         for (int m = 0; m < 4; ++m) {
;             const int row = rowb + ai * HALF + m * 16 + fr;
; #pragma unroll
;             for (int i = 0; i < 2; ++i) { const int c = lane + 64 * i; *(PG8_LAS u32x4*)(stg + (c >> 3) * 144 + (c & 7) * 16) = xin[m][i]; }
;             float ss = 0.f;
; #pragma unroll
;             for (int bj = 0; bj < 2; ++bj) {
;                 const u32x4 xo = *(const PG8_LAS u32x4*)(st + bj * 64);
;                 float v[8];
; #pragma unroll
;                 for (int i = 0; i < 4; ++i) { v[2 * i] = __uint_as_float(xo[i] << 16) + acc[ai][bj][m][i >> 1][(2 * i) & 3]; v[2 * i + 1] = __uint_as_float(xo[i] & 0xffff0000u) + acc[ai][bj][m][i >> 1][(2 * i + 1) & 3]; }
;                 u32x4 w; w.x = cvt_pk_bf16(v[0], v[1]); w.y = cvt_pk_bf16(v[2], v[3]); w.z = cvt_pk_bf16(v[4], v[5]); w.w = cvt_pk_bf16(v[6], v[7]);
;                 *(PG8_LAS u32x4*)(st + bj * 64) = w;
;                 ss += ((v[0] * v[0] + v[1] * v[1]) + (v[2] * v[2] + v[3] * v[3])) + ((v[4] * v[4] + v[5] * v[5]) + (v[6] * v[6] + v[7] * v[7]));
;             }
; #pragma unroll
;             for (int i = 0; i < 2; ++i) { const int c = lane + 64 * i; const u32x4 w = *(const PG8_LAS u32x4*)(stg + (c >> 3) * 144 + (c & 7) * 16);
;                 *(u32x4*)(xo_ + (size_t)(row - fr + (c >> 3)) * 1024 + colw + (c & 7) * 8) = w; }
;             ss = sum_x16(ss); ss = sum_x32(ss);
	v_lshlrev_b32_e32 v118, 16, v114
	v_and_b32_e32 v114, 0xffff0000, v114
	v_add_f32_e32 v111, v111, v114
	v_and_b32_e32 v114, 0xffff0000, v115
	v_add_f32_e32 v113, v113, v114
	v_lshlrev_b32_e32 v114, 16, v116
	v_add_f32_e32 v114, v106, v114
	v_and_b32_e32 v106, 0xffff0000, v116
	v_lshlrev_b32_e32 v119, 16, v115
	v_add_f32_e32 v115, v107, v106
	v_lshlrev_b32_e32 v106, 16, v117
	v_add_f32_e32 v116, v108, v106
	v_and_b32_e32 v106, 0xffff0000, v117
	v_add_f32_e32 v110, v110, v118
	v_add_f32_e32 v112, v112, v119
	v_add_f32_e32 v117, v109, v106
	v_cvt_pk_bf16_f32 v106, v110, v111
	v_cvt_pk_bf16_f32 v107, v112, v113
	v_cvt_pk_bf16_f32 v108, v114, v115
	v_cvt_pk_bf16_f32 v109, v116, v117
	ds_write_b128 v210, v[106:109]
	v_mul_f32_e32 v106, v111, v111
	v_mul_f32_e32 v107, v113, v113
	v_fmac_f32_e32 v106, v110, v110
	v_fmac_f32_e32 v107, v112, v112
	v_add_f32_e32 v110, v106, v107
	ds_read_b128 v[106:109], v210 offset:64
	v_mul_f32_e32 v111, v115, v115
	v_mul_f32_e32 v112, v117, v117
	v_fmac_f32_e32 v111, v114, v114
	v_fmac_f32_e32 v112, v116, v116
	v_add_f32_e32 v111, v111, v112
	v_add_f32_e32 v110, v110, v111
	s_waitcnt lgkmcnt(0)
	v_lshlrev_b32_e32 v111, 16, v106
	v_and_b32_e32 v106, 0xffff0000, v106
	v_add_f32_e32 v103, v103, v106
	v_lshlrev_b32_e32 v106, 16, v107
	v_add_f32_e32 v104, v104, v106
	v_and_b32_e32 v106, 0xffff0000, v107
	v_add_f32_e32 v105, v105, v106
	v_lshlrev_b32_e32 v106, 16, v108
	v_add_f32_e32 v106, v98, v106
	v_and_b32_e32 v98, 0xffff0000, v108
	v_add_f32_e32 v107, v99, v98
	v_lshlrev_b32_e32 v98, 16, v109
	v_add_f32_e32 v108, v100, v98
	v_and_b32_e32 v98, 0xffff0000, v109
	v_add_f32_e32 v102, v102, v111
	v_add_f32_e32 v109, v101, v98
	v_cvt_pk_bf16_f32 v98, v102, v103
	v_cvt_pk_bf16_f32 v99, v104, v105
	v_cvt_pk_bf16_f32 v100, v106, v107
	v_cvt_pk_bf16_f32 v101, v108, v109
	ds_write_b128 v210, v[98:101] offset:64
	v_mul_f32_e32 v98, v103, v103
	v_mul_f32_e32 v99, v105, v105
	v_fmac_f32_e32 v98, v102, v102
	v_fmac_f32_e32 v99, v104, v104
	v_add_f32_e32 v98, v98, v99
	v_mul_f32_e32 v99, v107, v107
	v_mul_f32_e32 v100, v109, v109
	v_fmac_f32_e32 v99, v106, v106
	v_fmac_f32_e32 v100, v108, v108
	v_add_f32_e32 v99, v99, v100
	v_add_f32_e32 v98, v98, v99
	v_add_f32_e32 v108, v110, v98
	ds_read_b128 v[98:101], v211
	v_lshl_add_u64 v[102:103], s[76:77], 0, v[194:195]
	v_lshl_add_u64 v[102:103], v[102:103], 0, s[48:49]
	v_lshl_add_u64 v[106:107], v[102:103], 0, v[0:1]
	ds_read_b128 v[102:105], v211 offset:1152
	s_waitcnt lgkmcnt(1)
	global_store_dwordx4 v[106:107], v[98:101], off nt
	s_nop 1
	v_lshl_add_u64 v[98:99], s[76:77], 0, v[192:193]
	v_lshl_add_u64 v[98:99], v[98:99], 0, s[48:49]
	v_lshl_add_u64 v[98:99], v[98:99], 0, v[0:1]
	s_waitcnt lgkmcnt(0)
	global_store_dwordx4 v[98:99], v[102:105], off nt
	v_mov_b32_e32 v98, v108
	s_nop 1
	v_permlane16_swap_b32_e32 v108, v98
	v_add_f32_e32 v98, v108, v98
	v_mov_b32_e32 v99, v98
	s_nop 1
	v_permlane32_swap_b32_e32 v98, v99
	v_add_f32_e32 v165, v98, v99
	ds_write_b128 v209, v[134:137]
	ds_write_b128 v209, v[138:141] offset:1152
	ds_read_b128 v[98:101], v210
	s_waitcnt lgkmcnt(0)
	v_lshlrev_b32_e32 v102, 16, v98
	v_and_b32_e32 v98, 0xffff0000, v98
	v_add_f32_e32 v95, v95, v98
	v_and_b32_e32 v98, 0xffff0000, v99
	v_add_f32_e32 v97, v97, v98
	v_lshlrev_b32_e32 v98, 16, v100
	v_add_f32_e32 v98, v90, v98
	v_and_b32_e32 v90, 0xffff0000, v100
	v_lshlrev_b32_e32 v103, 16, v99
	v_add_f32_e32 v99, v91, v90
	v_lshlrev_b32_e32 v90, 16, v101
	v_add_f32_e32 v100, v92, v90
	v_and_b32_e32 v90, 0xffff0000, v101
	v_add_f32_e32 v94, v94, v102
	v_add_f32_e32 v96, v96, v103
	v_add_f32_e32 v101, v93, v90
	v_cvt_pk_bf16_f32 v90, v94, v95
	v_cvt_pk_bf16_f32 v91, v96, v97
	v_cvt_pk_bf16_f32 v92, v98, v99
	v_cvt_pk_bf16_f32 v93, v100, v101
	ds_write_b128 v210, v[90:93]
	v_mul_f32_e32 v90, v95, v95
	v_mul_f32_e32 v91, v97, v97
	v_fmac_f32_e32 v90, v94, v94
	v_fmac_f32_e32 v91, v96, v96
	v_add_f32_e32 v94, v90, v91
	ds_read_b128 v[90:93], v210 offset:64
	v_mul_f32_e32 v95, v99, v99
	v_mul_f32_e32 v96, v101, v101
	v_fmac_f32_e32 v95, v98, v98
	v_fmac_f32_e32 v96, v100, v100
	v_add_f32_e32 v95, v95, v96
	v_add_f32_e32 v94, v94, v95
	s_waitcnt lgkmcnt(0)
	v_lshlrev_b32_e32 v95, 16, v90
	v_and_b32_e32 v90, 0xffff0000, v90
	v_add_f32_e32 v87, v87, v90
	v_lshlrev_b32_e32 v90, 16, v91
	v_add_f32_e32 v88, v88, v90
	v_and_b32_e32 v90, 0xffff0000, v91
	v_add_f32_e32 v89, v89, v90
	v_lshlrev_b32_e32 v90, 16, v92
	v_add_f32_e32 v90, v82, v90
	v_and_b32_e32 v82, 0xffff0000, v92
	v_add_f32_e32 v91, v83, v82
	v_lshlrev_b32_e32 v82, 16, v93
	v_add_f32_e32 v92, v84, v82
	v_and_b32_e32 v82, 0xffff0000, v93
	v_add_f32_e32 v86, v86, v95
	v_add_f32_e32 v93, v85, v82
	v_cvt_pk_bf16_f32 v82, v86, v87
	v_cvt_pk_bf16_f32 v83, v88, v89
	v_cvt_pk_bf16_f32 v84, v90, v91
	v_cvt_pk_bf16_f32 v85, v92, v93
	ds_write_b128 v210, v[82:85] offset:64
	v_mul_f32_e32 v82, v87, v87
	v_mul_f32_e32 v83, v89, v89
	v_fmac_f32_e32 v82, v86, v86
	v_fmac_f32_e32 v83, v88, v88
	v_add_f32_e32 v82, v82, v83
	v_mul_f32_e32 v83, v91, v91
	v_mul_f32_e32 v84, v93, v93
	v_fmac_f32_e32 v83, v90, v90
	v_fmac_f32_e32 v84, v92, v92
	v_add_f32_e32 v83, v83, v84
	v_add_f32_e32 v82, v82, v83
	v_add_f32_e32 v92, v94, v82
	ds_read_b128 v[82:85], v211
	v_lshl_add_u64 v[86:87], s[76:77], 0, v[188:189]
	v_lshl_add_u64 v[86:87], v[86:87], 0, s[48:49]
	v_lshl_add_u64 v[90:91], v[86:87], 0, v[0:1]
	ds_read_b128 v[86:89], v211 offset:1152
	s_waitcnt lgkmcnt(1)
	global_store_dwordx4 v[90:91], v[82:85], off nt
	s_nop 1
	v_lshl_add_u64 v[82:83], s[76:77], 0, v[186:187]
	v_lshl_add_u64 v[82:83], v[82:83], 0, s[48:49]
	v_lshl_add_u64 v[82:83], v[82:83], 0, v[0:1]
	s_waitcnt lgkmcnt(0)
; #define PG8_LAS __attribute__((address_space(3)))
; __device__ __forceinline__ unsigned cvt_pk_bf16(float lo, float hi) { unsigned r; asm volatile("v_cvt_pk_bf16_f32 %0, %1, %2" : "=v"(r) : "v"(lo), "v"(hi)); return r; }
; __device__ __forceinline__ float sum_x16(float s) { auto r = __builtin_amdgcn_permlane16_swap(__float_as_uint(s), __float_as_uint(s), false, false); return __uint_as_float(r[0]) + __uint_as_float(r[1]); }
;     __device__ __forceinline__ void operator()(const f32x4 (&acc)[2][2][4][2], const Unit& u, int wr, int wc, int fr, int fq, PG8_LAS unsigned char* stg) const {
;     ...
;             for (int i = 0; i < 2; ++i) { const int c = lane + 64 * i; xin[m][i] = *(const u32x4*)(xb + (size_t)(rowb + ai * HALF + m * 16 + (c >> 3)) * 1024 + colw + (c & 7) * 8); }
; #pragma unroll
;         for (int m = 0; m < 4; ++m) {
;             const int row = rowb + ai * HALF + m * 16 + fr;
; #pragma unroll
;             for (int i = 0; i < 2; ++i) { const int c = lane + 64 * i; *(PG8_LAS u32x4*)(stg + (c >> 3) * 144 + (c & 7) * 16) = xin[m][i]; }
;             float ss = 0.f;
; #pragma unroll
;             for (int bj = 0; bj < 2; ++bj) {
;                 const u32x4 xo = *(const PG8_LAS u32x4*)(st + bj * 64);
;                 float v[8];
; #pragma unroll
;                 for (int i = 0; i < 4; ++i) { v[2 * i] = __uint_as_float(xo[i] << 16) + acc[ai][bj][m][i >> 1][(2 * i) & 3]; v[2 * i + 1] = __uint_as_float(xo[i] & 0xffff0000u) + acc[ai][bj][m][i >> 1][(2 * i + 1) & 3]; }
;                 u32x4 w; w.x = cvt_pk_bf16(v[0], v[1]); w.y = cvt_pk_bf16(v[2], v[3]); w.z = cvt_pk_bf16(v[4], v[5]); w.w = cvt_pk_bf16(v[6], v[7]);
;                 *(PG8_LAS u32x4*)(st + bj * 64) = w;
;                 ss += ((v[0] * v[0] + v[1] * v[1]) + (v[2] * v[2] + v[3] * v[3])) + ((v[4] * v[4] + v[5] * v[5]) + (v[6] * v[6] + v[7] * v[7]));
;             }
; #pragma unroll
;             for (int i = 0; i < 2; ++i) { const int c = lane + 64 * i; const u32x4 w = *(const PG8_LAS u32x4*)(stg + (c >> 3) * 144 + (c & 7) * 16);
;                 *(u32x4*)(xo_ + (size_t)(row - fr + (c >> 3)) * 1024 + colw + (c & 7) * 8) = w; }
;             ss = sum_x16(ss); ss = sum_x32(ss);
;             if (fq == 0) po_[(size_t)(u.pn * 4 + wc) * 65536 + row] = ss;
	global_store_dwordx4 v[82:83], v[86:89], off nt
	v_mov_b32_e32 v82, v92
	s_nop 1
	v_permlane16_swap_b32_e32 v92, v82
	v_add_f32_e32 v82, v92, v82
	v_mov_b32_e32 v83, v82
	s_nop 1
	v_permlane32_swap_b32_e32 v82, v83
	v_readlane_b32 s55, v254, 41
	v_add_f32_e32 v166, v82, v83
	ds_write_b128 v209, v[130:133]
	ds_write_b128 v209, v[142:145] offset:1152
	ds_read_b128 v[82:85], v210
	s_waitcnt lgkmcnt(0)
	v_lshlrev_b32_e32 v86, 16, v82
	v_and_b32_e32 v82, 0xffff0000, v82
	v_add_f32_e32 v79, v79, v82
	v_and_b32_e32 v82, 0xffff0000, v83
	v_add_f32_e32 v81, v81, v82
	v_lshlrev_b32_e32 v82, 16, v84
	v_add_f32_e32 v82, v74, v82
	v_and_b32_e32 v74, 0xffff0000, v84
	v_lshlrev_b32_e32 v87, 16, v83
	v_add_f32_e32 v83, v75, v74
	v_lshlrev_b32_e32 v74, 16, v85
	v_add_f32_e32 v84, v76, v74
	v_and_b32_e32 v74, 0xffff0000, v85
	v_add_f32_e32 v78, v78, v86
	v_add_f32_e32 v80, v80, v87
	v_add_f32_e32 v85, v77, v74
	v_cvt_pk_bf16_f32 v74, v78, v79
	v_cvt_pk_bf16_f32 v75, v80, v81
	v_cvt_pk_bf16_f32 v76, v82, v83
	v_cvt_pk_bf16_f32 v77, v84, v85
	ds_write_b128 v210, v[74:77]
	v_mul_f32_e32 v74, v79, v79
	v_mul_f32_e32 v75, v81, v81
	v_fmac_f32_e32 v74, v78, v78
	v_fmac_f32_e32 v75, v80, v80
	v_add_f32_e32 v78, v74, v75
	ds_read_b128 v[74:77], v210 offset:64
	v_mul_f32_e32 v79, v83, v83
	v_mul_f32_e32 v80, v85, v85
	v_fmac_f32_e32 v79, v82, v82
	v_fmac_f32_e32 v80, v84, v84
	v_add_f32_e32 v79, v79, v80
	v_add_f32_e32 v78, v78, v79
	s_waitcnt lgkmcnt(0)
	v_lshlrev_b32_e32 v79, 16, v74
	v_and_b32_e32 v74, 0xffff0000, v74
	v_add_f32_e32 v71, v71, v74
	v_lshlrev_b32_e32 v74, 16, v75
	v_add_f32_e32 v72, v72, v74
	v_and_b32_e32 v74, 0xffff0000, v75
	v_add_f32_e32 v73, v73, v74
	v_lshlrev_b32_e32 v74, 16, v76
	v_add_f32_e32 v74, v66, v74
	v_and_b32_e32 v66, 0xffff0000, v76
	v_add_f32_e32 v75, v67, v66
	v_lshlrev_b32_e32 v66, 16, v77
	v_add_f32_e32 v76, v68, v66
	v_and_b32_e32 v66, 0xffff0000, v77
	v_add_f32_e32 v70, v70, v79
	v_add_f32_e32 v77, v69, v66
	v_cvt_pk_bf16_f32 v66, v70, v71
	v_cvt_pk_bf16_f32 v67, v72, v73
	v_cvt_pk_bf16_f32 v68, v74, v75
	v_cvt_pk_bf16_f32 v69, v76, v77
	ds_write_b128 v210, v[66:69] offset:64
	v_mul_f32_e32 v66, v71, v71
	v_mul_f32_e32 v67, v73, v73
	v_fmac_f32_e32 v66, v70, v70
	v_fmac_f32_e32 v67, v72, v72
	v_add_f32_e32 v66, v66, v67
	v_mul_f32_e32 v67, v75, v75
	v_mul_f32_e32 v68, v77, v77
	v_fmac_f32_e32 v67, v74, v74
	v_fmac_f32_e32 v68, v76, v76
	v_add_f32_e32 v67, v67, v68
	v_add_f32_e32 v66, v66, v67
	v_add_f32_e32 v76, v78, v66
	ds_read_b128 v[66:69], v211
	v_lshl_add_u64 v[70:71], s[76:77], 0, v[184:185]
	v_lshl_add_u64 v[70:71], v[70:71], 0, s[48:49]
	v_lshl_add_u64 v[74:75], v[70:71], 0, v[0:1]
	ds_read_b128 v[70:73], v211 offset:1152
	s_waitcnt lgkmcnt(1)
	global_store_dwordx4 v[74:75], v[66:69], off nt
	s_nop 1
	v_lshl_add_u64 v[66:67], s[76:77], 0, v[190:191]
	v_lshl_add_u64 v[66:67], v[66:67], 0, s[48:49]
	v_lshl_add_u64 v[66:67], v[66:67], 0, v[0:1]
	s_waitcnt lgkmcnt(0)
	global_store_dwordx4 v[66:67], v[70:73], off nt
	v_mov_b32_e32 v66, v76
	s_nop 1
	v_permlane16_swap_b32_e32 v76, v66
	v_add_f32_e32 v66, v76, v66
	v_mov_b32_e32 v67, v66
	s_nop 1
	v_permlane32_swap_b32_e32 v66, v67
	v_add_f32_e32 v167, v66, v67
	v_mbcnt_lo_u32_b32 v200, -1, 0
	v_mbcnt_hi_u32_b32 v200, -1, v200
	v_lshrrev_b32_e32 v201, 4, v200
	v_cmp_eq_u32_e64 s[100:101], 1, v201
	s_nop 1
	v_cndmask_b32_e64 v212, v164, v165, s[100:101]
	v_cmp_eq_u32_e64 s[100:101], 2, v201
	s_nop 1
	v_cndmask_b32_e64 v212, v212, v166, s[100:101]
	v_cmp_eq_u32_e64 s[100:101], 3, v201
	s_nop 1
	v_cndmask_b32_e64 v212, v212, v167, s[100:101]
	s_nop 1
	s_add_u32 s100, s82, s46
	s_addc_u32 s101, s83, s47
	v_or_b32_e32 v201, s44, v174
	v_lshlrev_b32_e32 v201, 2, v201
	v_and_b32_e32 v200, 48, v200
	v_lshl_add_u32 v201, v200, 2, v201
	global_store_dword v201, v212, s[100:101] offset:0
	s_add_i32 s29, s44, 0x80
	v_or_b32_e32 v66, s29, v206
	v_ashrrev_i32_e32 v67, 31, v66
	v_lshlrev_b64 v[104:105], 11, v[66:67]
	v_lshl_add_u64 v[66:67], v[182:183], 0, v[104:105]
	global_load_dwordx4 v[106:109], v[66:67], off nt
	v_or_b32_e32 v66, s29, v207
	v_ashrrev_i32_e32 v67, 31, v66
	v_lshlrev_b64 v[102:103], 11, v[66:67]
	v_lshl_add_u64 v[66:67], v[182:183], 0, v[102:103]
	global_load_dwordx4 v[110:113], v[66:67], off nt
	s_add_i32 s29, s44, 0x90
	v_or_b32_e32 v66, s29, v206
	v_ashrrev_i32_e32 v67, 31, v66
	v_lshlrev_b64 v[100:101], 11, v[66:67]
	v_lshl_add_u64 v[66:67], v[182:183], 0, v[100:101]
	global_load_dwordx4 v[82:85], v[66:67], off nt
	v_or_b32_e32 v66, s29, v207
	v_ashrrev_i32_e32 v67, 31, v66
	v_lshlrev_b64 v[98:99], 11, v[66:67]
	v_lshl_add_u64 v[66:67], v[182:183], 0, v[98:99]
	s_add_i32 s29, s44, 0xa0
	global_load_dwordx4 v[86:89], v[66:67], off nt
	v_or_b32_e32 v66, s29, v206
	v_ashrrev_i32_e32 v67, 31, v66
	v_lshlrev_b64 v[94:95], 11, v[66:67]
	v_lshl_add_u64 v[66:67], v[182:183], 0, v[94:95]
	global_load_dwordx4 v[70:73], v[66:67], off nt
	v_or_b32_e32 v66, s29, v207
	v_ashrrev_i32_e32 v67, 31, v66
	v_lshlrev_b64 v[92:93], 11, v[66:67]
	v_lshl_add_u64 v[66:67], v[182:183], 0, v[92:93]
	s_add_i32 s29, s44, 0xb0
	global_load_dwordx4 v[74:77], v[66:67], off nt
	v_or_b32_e32 v66, s29, v206
	v_or_b32_e32 v78, s29, v207
	v_ashrrev_i32_e32 v67, 31, v66
	v_ashrrev_i32_e32 v79, 31, v78
	v_lshlrev_b64 v[90:91], 11, v[66:67]
	v_lshlrev_b64 v[96:97], 11, v[78:79]
	v_lshl_add_u64 v[66:67], v[182:183], 0, v[90:91]
	v_lshl_add_u64 v[78:79], v[182:183], 0, v[96:97]
	global_load_dwordx4 v[66:69], v[66:67], off nt
	s_nop 0
	global_load_dwordx4 v[78:81], v[78:79], off nt
	s_waitcnt vmcnt(7)
	ds_write_b128 v209, v[106:109]
	s_waitcnt vmcnt(6)
; #define PG8_LAS __attribute__((address_space(3)))
; __device__ __forceinline__ unsigned cvt_pk_bf16(float lo, float hi) { unsigned r; asm volatile("v_cvt_pk_bf16_f32 %0, %1, %2" : "=v"(r) : "v"(lo), "v"(hi)); return r; }
; __device__ __forceinline__ float sum_x16(float s) { auto r = __builtin_amdgcn_permlane16_swap(__float_as_uint(s), __float_as_uint(s), false, false); return __uint_as_float(r[0]) + __uint_as_float(r[1]); }
; __device__ __forceinline__ float sum_x32(float s) { auto r = __builtin_amdgcn_permlane32_swap(__float_as_uint(s), __float_as_uint(s), false, false); return __uint_as_float(r[0]) + __uint_as_float(r[1]); }
;     __device__ __forceinline__ void operator()(const f32x4 (&acc)[2][2][4][2], const Unit& u, int wr, int wc, int fr, int fq, PG8_LAS unsigned char* stg) const {
;     ...
;         for (int m = 0; m < 4; ++m) {
;             const int row = rowb + ai * HALF + m * 16 + fr;
; #pragma unroll
;             for (int i = 0; i < 2; ++i) { const int c = lane + 64 * i; *(PG8_LAS u32x4*)(stg + (c >> 3) * 144 + (c & 7) * 16) = xin[m][i]; }
;             float ss = 0.f;
; #pragma unroll
;             for (int bj = 0; bj < 2; ++bj) {
;                 const u32x4 xo = *(const PG8_LAS u32x4*)(st + bj * 64);
;                 float v[8];
; #pragma unroll
;                 for (int i = 0; i < 4; ++i) { v[2 * i] = __uint_as_float(xo[i] << 16) + acc[ai][bj][m][i >> 1][(2 * i) & 3]; v[2 * i + 1] = __uint_as_float(xo[i] & 0xffff0000u) + acc[ai][bj][m][i >> 1][(2 * i + 1) & 3]; }
;                 u32x4 w; w.x = cvt_pk_bf16(v[0], v[1]); w.y = cvt_pk_bf16(v[2], v[3]); w.z = cvt_pk_bf16(v[4], v[5]); w.w = cvt_pk_bf16(v[6], v[7]);
;                 *(PG8_LAS u32x4*)(st + bj * 64) = w;
;                 ss += ((v[0] * v[0] + v[1] * v[1]) + (v[2] * v[2] + v[3] * v[3])) + ((v[4] * v[4] + v[5] * v[5]) + (v[6] * v[6] + v[7] * v[7]));
;             }
; #pragma unroll
;             for (int i = 0; i < 2; ++i) { const int c = lane + 64 * i; const u32x4 w = *(const PG8_LAS u32x4*)(stg + (c >> 3) * 144 + (c & 7) * 16);
;                 *(u32x4*)(xo_ + (size_t)(row - fr + (c >> 3)) * 1024 + colw + (c & 7) * 8) = w; }
;             ss = sum_x16(ss); ss = sum_x32(ss);
	ds_write_b128 v209, v[110:113] offset:1152
	ds_read_b128 v[106:109], v210
	s_waitcnt lgkmcnt(0)
	v_lshlrev_b32_e32 v110, 16, v106
	v_and_b32_e32 v106, 0xffff0000, v106
	v_add_f32_e32 v63, v63, v106
	v_lshlrev_b32_e32 v106, 16, v107
	v_add_f32_e32 v64, v64, v106
	v_and_b32_e32 v106, 0xffff0000, v107
	v_add_f32_e32 v65, v65, v106
	v_lshlrev_b32_e32 v106, 16, v108
	v_add_f32_e32 v106, v58, v106
	v_and_b32_e32 v58, 0xffff0000, v108
	v_add_f32_e32 v107, v59, v58
	v_lshlrev_b32_e32 v58, 16, v109
	v_add_f32_e32 v108, v60, v58
	v_and_b32_e32 v58, 0xffff0000, v109
	v_add_f32_e32 v62, v62, v110
	v_add_f32_e32 v109, v61, v58
	v_cvt_pk_bf16_f32 v58, v62, v63
	v_cvt_pk_bf16_f32 v59, v64, v65
	v_cvt_pk_bf16_f32 v60, v106, v107
	v_cvt_pk_bf16_f32 v61, v108, v109
	ds_write_b128 v210, v[58:61]
	v_mul_f32_e32 v58, v63, v63
	v_mul_f32_e32 v59, v65, v65
	v_fmac_f32_e32 v58, v62, v62
	v_fmac_f32_e32 v59, v64, v64
	v_add_f32_e32 v58, v58, v59
	v_mul_f32_e32 v59, v107, v107
	v_mul_f32_e32 v60, v109, v109
	v_fmac_f32_e32 v59, v106, v106
	v_fmac_f32_e32 v60, v108, v108
	v_add_f32_e32 v59, v59, v60
	v_add_f32_e32 v62, v58, v59
	ds_read_b128 v[58:61], v210 offset:64
	s_waitcnt lgkmcnt(0)
	v_lshlrev_b32_e32 v63, 16, v58
	v_and_b32_e32 v58, 0xffff0000, v58
	v_add_f32_e32 v55, v55, v58
	v_lshlrev_b32_e32 v58, 16, v59
	v_add_f32_e32 v56, v56, v58
	v_and_b32_e32 v58, 0xffff0000, v59
	v_add_f32_e32 v57, v57, v58
	v_lshlrev_b32_e32 v58, 16, v60
	v_add_f32_e32 v58, v50, v58
	v_and_b32_e32 v50, 0xffff0000, v60
	v_add_f32_e32 v59, v51, v50
	v_lshlrev_b32_e32 v50, 16, v61
	v_add_f32_e32 v60, v52, v50
	v_and_b32_e32 v50, 0xffff0000, v61
	v_add_f32_e32 v54, v54, v63
	v_add_f32_e32 v61, v53, v50
	v_cvt_pk_bf16_f32 v50, v54, v55
	v_cvt_pk_bf16_f32 v51, v56, v57
	v_cvt_pk_bf16_f32 v52, v58, v59
	v_cvt_pk_bf16_f32 v53, v60, v61
	ds_write_b128 v210, v[50:53] offset:64
	v_mul_f32_e32 v50, v55, v55
	v_mul_f32_e32 v51, v57, v57
	v_fmac_f32_e32 v50, v54, v54
	v_fmac_f32_e32 v51, v56, v56
	v_add_f32_e32 v50, v50, v51
	v_mul_f32_e32 v51, v59, v59
	v_mul_f32_e32 v52, v61, v61
	v_fmac_f32_e32 v51, v58, v58
	v_fmac_f32_e32 v52, v60, v60
	v_add_f32_e32 v51, v51, v52
	v_add_f32_e32 v50, v50, v51
	v_add_f32_e32 v56, v62, v50
	ds_read_b128 v[50:53], v211
	v_lshl_add_u64 v[54:55], s[76:77], 0, v[104:105]
	v_lshl_add_u64 v[54:55], v[54:55], 0, s[48:49]
	v_lshl_add_u64 v[54:55], v[54:55], 0, v[0:1]
	s_waitcnt lgkmcnt(0)
	global_store_dwordx4 v[54:55], v[50:53], off nt
	ds_read_b128 v[50:53], v211 offset:1152
	v_lshl_add_u64 v[54:55], s[76:77], 0, v[102:103]
	v_lshl_add_u64 v[54:55], v[54:55], 0, s[48:49]
	v_lshl_add_u64 v[54:55], v[54:55], 0, v[0:1]
	s_waitcnt lgkmcnt(0)
	global_store_dwordx4 v[54:55], v[50:53], off nt
	s_nop 1
	v_mov_b32_e32 v50, v56
	s_nop 1
	v_permlane16_swap_b32_e32 v56, v50
	v_add_f32_e32 v50, v56, v50
	v_mov_b32_e32 v51, v50
	s_nop 1
	v_permlane32_swap_b32_e32 v50, v51
	v_add_f32_e32 v164, v50, v51
	s_waitcnt vmcnt(7)
	ds_write_b128 v209, v[82:85]
	s_waitcnt vmcnt(6)
	ds_write_b128 v209, v[86:89] offset:1152
	ds_read_b128 v[50:53], v210
	s_waitcnt lgkmcnt(0)
	v_lshlrev_b32_e32 v54, 16, v50
	v_and_b32_e32 v50, 0xffff0000, v50
	v_add_f32_e32 v47, v47, v50
	v_and_b32_e32 v50, 0xffff0000, v51
	v_add_f32_e32 v49, v49, v50
	v_lshlrev_b32_e32 v50, 16, v52
	v_add_f32_e32 v50, v42, v50
	v_and_b32_e32 v42, 0xffff0000, v52
	v_lshlrev_b32_e32 v55, 16, v51
	v_add_f32_e32 v51, v43, v42
	v_lshlrev_b32_e32 v42, 16, v53
	v_add_f32_e32 v52, v44, v42
	v_and_b32_e32 v42, 0xffff0000, v53
	v_add_f32_e32 v46, v46, v54
	v_add_f32_e32 v48, v48, v55
	v_add_f32_e32 v53, v45, v42
	v_cvt_pk_bf16_f32 v42, v46, v47
	v_cvt_pk_bf16_f32 v43, v48, v49
	v_cvt_pk_bf16_f32 v44, v50, v51
	v_cvt_pk_bf16_f32 v45, v52, v53
	ds_write_b128 v210, v[42:45]
	v_mul_f32_e32 v42, v47, v47
	v_mul_f32_e32 v43, v49, v49
	v_fmac_f32_e32 v42, v46, v46
	v_fmac_f32_e32 v43, v48, v48
	v_add_f32_e32 v46, v42, v43
	ds_read_b128 v[42:45], v210 offset:64
	v_mul_f32_e32 v47, v51, v51
	v_mul_f32_e32 v48, v53, v53
	v_fmac_f32_e32 v47, v50, v50
	v_fmac_f32_e32 v48, v52, v52
	v_add_f32_e32 v47, v47, v48
	v_add_f32_e32 v46, v46, v47
	s_waitcnt lgkmcnt(0)
	v_lshlrev_b32_e32 v47, 16, v42
	v_and_b32_e32 v42, 0xffff0000, v42
	v_add_f32_e32 v39, v39, v42
	v_lshlrev_b32_e32 v42, 16, v43
	v_add_f32_e32 v40, v40, v42
	v_and_b32_e32 v42, 0xffff0000, v43
	v_add_f32_e32 v41, v41, v42
	v_lshlrev_b32_e32 v42, 16, v44
	v_add_f32_e32 v42, v34, v42
	v_and_b32_e32 v34, 0xffff0000, v44
	v_add_f32_e32 v43, v35, v34
	v_lshlrev_b32_e32 v34, 16, v45
	v_add_f32_e32 v44, v36, v34
	v_and_b32_e32 v34, 0xffff0000, v45
	v_add_f32_e32 v38, v38, v47
	v_add_f32_e32 v45, v37, v34
	v_cvt_pk_bf16_f32 v34, v38, v39
	v_cvt_pk_bf16_f32 v35, v40, v41
	v_cvt_pk_bf16_f32 v36, v42, v43
	v_cvt_pk_bf16_f32 v37, v44, v45
	ds_write_b128 v210, v[34:37] offset:64
	v_mul_f32_e32 v34, v39, v39
	v_mul_f32_e32 v35, v41, v41
	v_fmac_f32_e32 v34, v38, v38
	v_fmac_f32_e32 v35, v40, v40
	v_add_f32_e32 v34, v34, v35
	v_mul_f32_e32 v35, v43, v43
	v_mul_f32_e32 v36, v45, v45
	v_fmac_f32_e32 v35, v42, v42
	v_fmac_f32_e32 v36, v44, v44
	v_add_f32_e32 v35, v35, v36
	v_add_f32_e32 v34, v34, v35
	v_add_f32_e32 v44, v46, v34
	ds_read_b128 v[34:37], v211
	v_lshl_add_u64 v[38:39], s[76:77], 0, v[100:101]
	v_lshl_add_u64 v[38:39], v[38:39], 0, s[48:49]
	v_lshl_add_u64 v[42:43], v[38:39], 0, v[0:1]
	ds_read_b128 v[38:41], v211 offset:1152
	s_waitcnt lgkmcnt(1)
	global_store_dwordx4 v[42:43], v[34:37], off nt
	s_nop 1
	v_lshl_add_u64 v[34:35], s[76:77], 0, v[98:99]
	v_lshl_add_u64 v[34:35], v[34:35], 0, s[48:49]
	v_lshl_add_u64 v[34:35], v[34:35], 0, v[0:1]
	s_waitcnt lgkmcnt(0)
; #define PG8_LAS __attribute__((address_space(3)))
; __device__ __forceinline__ unsigned cvt_pk_bf16(float lo, float hi) { unsigned r; asm volatile("v_cvt_pk_bf16_f32 %0, %1, %2" : "=v"(r) : "v"(lo), "v"(hi)); return r; }
; #define PG8_BAR __builtin_amdgcn_s_barrier()
;     __device__ __forceinline__ void operator()(const f32x4 (&acc)[2][2][4][2], const Unit& u, int wr, int wc, int fr, int fq, PG8_LAS unsigned char* stg) const {
;     ...
;         for (int m = 0; m < 4; ++m) {
;             const int row = rowb + ai * HALF + m * 16 + fr;
; #pragma unroll
;             for (int i = 0; i < 2; ++i) { const int c = lane + 64 * i; *(PG8_LAS u32x4*)(stg + (c >> 3) * 144 + (c & 7) * 16) = xin[m][i]; }
;             float ss = 0.f;
; #pragma unroll
;             for (int bj = 0; bj < 2; ++bj) {
;                 const u32x4 xo = *(const PG8_LAS u32x4*)(st + bj * 64);
;                 float v[8];
; #pragma unroll
;                 for (int i = 0; i < 4; ++i) { v[2 * i] = __uint_as_float(xo[i] << 16) + acc[ai][bj][m][i >> 1][(2 * i) & 3]; v[2 * i + 1] = __uint_as_float(xo[i] & 0xffff0000u) + acc[ai][bj][m][i >> 1][(2 * i + 1) & 3]; }
;                 u32x4 w; w.x = cvt_pk_bf16(v[0], v[1]); w.y = cvt_pk_bf16(v[2], v[3]); w.z = cvt_pk_bf16(v[4], v[5]); w.w = cvt_pk_bf16(v[6], v[7]);
;                 *(PG8_LAS u32x4*)(st + bj * 64) = w;
;                 ss += ((v[0] * v[0] + v[1] * v[1]) + (v[2] * v[2] + v[3] * v[3])) + ((v[4] * v[4] + v[5] * v[5]) + (v[6] * v[6] + v[7] * v[7]));
;             }
; #pragma unroll
;             for (int i = 0; i < 2; ++i) { const int c = lane + 64 * i; const u32x4 w = *(const PG8_LAS u32x4*)(stg + (c >> 3) * 144 + (c & 7) * 16);
;                 *(u32x4*)(xo_ + (size_t)(row - fr + (c >> 3)) * 1024 + colw + (c & 7) * 8) = w; }
;             ss = sum_x16(ss); ss = sum_x32(ss);
;             if (fq == 0) po_[(size_t)(u.pn * 4 + wc) * 65536 + row] = ss;
; template <class Epi, class Sched, bool ALIGN_EPI = false, bool SP2 = false>
; __device__ __forceinline__ void gemm_phase(PG8_LAS unsigned char* lds, const Gemm g, const Sched& S, const Epi& E, const int wave_s) {
;     ...
;         if (nxt.pm != cur.pm) rs_par ^= 1;
;         cur = nxt; cA = nA; cB = nB; ++ui;
;         if constexpr (ALIGN_EPI) { if (wr == 1) PG8_BAR; }
	global_store_dwordx4 v[34:35], v[38:41], off nt
	v_mov_b32_e32 v34, v44
	s_nop 1
	v_permlane16_swap_b32_e32 v44, v34
	v_add_f32_e32 v34, v44, v34
	v_mov_b32_e32 v35, v34
	s_nop 1
	v_permlane32_swap_b32_e32 v34, v35
	v_add_f32_e32 v165, v34, v35
	s_waitcnt vmcnt(7)
	ds_write_b128 v209, v[70:73]
	s_waitcnt vmcnt(6)
	ds_write_b128 v209, v[74:77] offset:1152
	ds_read_b128 v[34:37], v210
	s_waitcnt lgkmcnt(0)
	v_lshlrev_b32_e32 v38, 16, v34
	v_and_b32_e32 v34, 0xffff0000, v34
	v_add_f32_e32 v31, v31, v34
	v_and_b32_e32 v34, 0xffff0000, v35
	v_add_f32_e32 v33, v33, v34
	v_lshlrev_b32_e32 v34, 16, v36
	v_add_f32_e32 v34, v26, v34
	v_and_b32_e32 v26, 0xffff0000, v36
	v_lshlrev_b32_e32 v39, 16, v35
	v_add_f32_e32 v35, v27, v26
	v_lshlrev_b32_e32 v26, 16, v37
	v_add_f32_e32 v36, v28, v26
	v_and_b32_e32 v26, 0xffff0000, v37
	v_add_f32_e32 v30, v30, v38
	v_add_f32_e32 v32, v32, v39
	v_add_f32_e32 v37, v29, v26
	v_cvt_pk_bf16_f32 v26, v30, v31
	v_cvt_pk_bf16_f32 v27, v32, v33
	v_cvt_pk_bf16_f32 v28, v34, v35
	v_cvt_pk_bf16_f32 v29, v36, v37
	ds_write_b128 v210, v[26:29]
	v_mul_f32_e32 v26, v31, v31
	v_mul_f32_e32 v27, v33, v33
	v_fmac_f32_e32 v26, v30, v30
	v_fmac_f32_e32 v27, v32, v32
	v_add_f32_e32 v30, v26, v27
	ds_read_b128 v[26:29], v210 offset:64
	v_mul_f32_e32 v31, v35, v35
	v_mul_f32_e32 v32, v37, v37
	v_fmac_f32_e32 v31, v34, v34
	v_fmac_f32_e32 v32, v36, v36
	v_add_f32_e32 v31, v31, v32
	v_add_f32_e32 v30, v30, v31
	s_waitcnt lgkmcnt(0)
	v_lshlrev_b32_e32 v31, 16, v26
	v_and_b32_e32 v26, 0xffff0000, v26
	v_add_f32_e32 v23, v23, v26
	v_lshlrev_b32_e32 v26, 16, v27
	v_add_f32_e32 v24, v24, v26
	v_and_b32_e32 v26, 0xffff0000, v27
	v_add_f32_e32 v25, v25, v26
	v_lshlrev_b32_e32 v26, 16, v28
	v_add_f32_e32 v26, v18, v26
	v_and_b32_e32 v18, 0xffff0000, v28
	v_add_f32_e32 v27, v19, v18
	v_lshlrev_b32_e32 v18, 16, v29
	v_add_f32_e32 v28, v20, v18
	v_and_b32_e32 v18, 0xffff0000, v29
	v_add_f32_e32 v22, v22, v31
	v_add_f32_e32 v29, v21, v18
	v_cvt_pk_bf16_f32 v18, v22, v23
	v_cvt_pk_bf16_f32 v19, v24, v25
	v_cvt_pk_bf16_f32 v20, v26, v27
	v_cvt_pk_bf16_f32 v21, v28, v29
	ds_write_b128 v210, v[18:21] offset:64
	v_mul_f32_e32 v18, v23, v23
	v_mul_f32_e32 v19, v25, v25
	v_fmac_f32_e32 v18, v22, v22
	v_fmac_f32_e32 v19, v24, v24
	v_add_f32_e32 v18, v18, v19
	v_mul_f32_e32 v19, v27, v27
	v_mul_f32_e32 v20, v29, v29
	v_fmac_f32_e32 v19, v26, v26
	v_fmac_f32_e32 v20, v28, v28
	v_add_f32_e32 v19, v19, v20
	v_add_f32_e32 v18, v18, v19
	v_add_f32_e32 v28, v30, v18
	ds_read_b128 v[18:21], v211
	v_lshl_add_u64 v[22:23], s[76:77], 0, v[94:95]
	v_lshl_add_u64 v[22:23], v[22:23], 0, s[48:49]
	v_lshl_add_u64 v[26:27], v[22:23], 0, v[0:1]
	ds_read_b128 v[22:25], v211 offset:1152
	s_waitcnt lgkmcnt(1)
	global_store_dwordx4 v[26:27], v[18:21], off nt
	s_nop 1
	v_lshl_add_u64 v[18:19], s[76:77], 0, v[92:93]
	v_lshl_add_u64 v[18:19], v[18:19], 0, s[48:49]
	v_lshl_add_u64 v[18:19], v[18:19], 0, v[0:1]
	s_waitcnt lgkmcnt(0)
	global_store_dwordx4 v[18:19], v[22:25], off nt
	v_mov_b32_e32 v18, v28
	s_nop 1
	v_permlane16_swap_b32_e32 v28, v18
	v_add_f32_e32 v18, v28, v18
	v_mov_b32_e32 v19, v18
	s_nop 1
	v_permlane32_swap_b32_e32 v18, v19
	v_add_f32_e32 v166, v18, v19
	s_waitcnt vmcnt(7)
	ds_write_b128 v209, v[66:69]
	s_waitcnt vmcnt(6)
	ds_write_b128 v209, v[78:81] offset:1152
	ds_read_b128 v[18:21], v210
	s_waitcnt lgkmcnt(0)
	v_lshlrev_b32_e32 v22, 16, v18
	v_and_b32_e32 v18, 0xffff0000, v18
	v_add_f32_e32 v15, v15, v18
	v_and_b32_e32 v18, 0xffff0000, v19
	v_add_f32_e32 v17, v17, v18
	v_lshlrev_b32_e32 v18, 16, v20
	v_add_f32_e32 v18, v10, v18
	v_and_b32_e32 v10, 0xffff0000, v20
	v_lshlrev_b32_e32 v23, 16, v19
	v_add_f32_e32 v19, v11, v10
	v_lshlrev_b32_e32 v10, 16, v21
	v_add_f32_e32 v20, v12, v10
	v_and_b32_e32 v10, 0xffff0000, v21
	v_add_f32_e32 v14, v14, v22
	v_add_f32_e32 v16, v16, v23
	v_add_f32_e32 v21, v13, v10
	v_cvt_pk_bf16_f32 v10, v14, v15
	v_cvt_pk_bf16_f32 v11, v16, v17
	v_cvt_pk_bf16_f32 v12, v18, v19
	v_cvt_pk_bf16_f32 v13, v20, v21
	ds_write_b128 v210, v[10:13]
	v_mul_f32_e32 v10, v15, v15
	v_mul_f32_e32 v11, v17, v17
	v_fmac_f32_e32 v10, v14, v14
	v_fmac_f32_e32 v11, v16, v16
	v_add_f32_e32 v14, v10, v11
	ds_read_b128 v[10:13], v210 offset:64
	v_mul_f32_e32 v15, v19, v19
	v_mul_f32_e32 v16, v21, v21
	v_fmac_f32_e32 v15, v18, v18
	v_fmac_f32_e32 v16, v20, v20
	v_add_f32_e32 v15, v15, v16
	v_add_f32_e32 v14, v14, v15
	s_waitcnt lgkmcnt(0)
	v_lshlrev_b32_e32 v15, 16, v10
	v_and_b32_e32 v10, 0xffff0000, v10
	v_add_f32_e32 v7, v7, v10
	v_lshlrev_b32_e32 v10, 16, v11
	v_add_f32_e32 v8, v8, v10
	v_and_b32_e32 v10, 0xffff0000, v11
	v_add_f32_e32 v9, v9, v10
	v_lshlrev_b32_e32 v10, 16, v12
	v_add_f32_e32 v10, v2, v10
	v_and_b32_e32 v2, 0xffff0000, v12
	v_add_f32_e32 v11, v3, v2
	v_lshlrev_b32_e32 v2, 16, v13
	v_add_f32_e32 v12, v4, v2
	v_and_b32_e32 v2, 0xffff0000, v13
	v_add_f32_e32 v6, v6, v15
	v_add_f32_e32 v13, v5, v2
	v_cvt_pk_bf16_f32 v2, v6, v7
	v_cvt_pk_bf16_f32 v3, v8, v9
	v_cvt_pk_bf16_f32 v4, v10, v11
	v_cvt_pk_bf16_f32 v5, v12, v13
	ds_write_b128 v210, v[2:5] offset:64
	v_mul_f32_e32 v2, v7, v7
	v_mul_f32_e32 v3, v9, v9
	v_fmac_f32_e32 v2, v6, v6
	v_fmac_f32_e32 v3, v8, v8
	v_add_f32_e32 v2, v2, v3
	v_mul_f32_e32 v3, v11, v11
	v_mul_f32_e32 v4, v13, v13
	v_fmac_f32_e32 v3, v10, v10
	v_fmac_f32_e32 v4, v12, v12
	v_add_f32_e32 v3, v3, v4
	v_add_f32_e32 v2, v2, v3
	v_add_f32_e32 v12, v14, v2
	ds_read_b128 v[2:5], v211
	v_lshl_add_u64 v[6:7], s[76:77], 0, v[90:91]
	v_lshl_add_u64 v[6:7], v[6:7], 0, s[48:49]
	v_lshl_add_u64 v[10:11], v[6:7], 0, v[0:1]
	ds_read_b128 v[6:9], v211 offset:1152
	s_waitcnt lgkmcnt(1)
	global_store_dwordx4 v[10:11], v[2:5], off nt
	s_nop 1
	v_lshl_add_u64 v[2:3], s[76:77], 0, v[96:97]
	v_lshl_add_u64 v[2:3], v[2:3], 0, s[48:49]
	v_lshl_add_u64 v[2:3], v[2:3], 0, v[0:1]
	s_waitcnt lgkmcnt(0)
	global_store_dwordx4 v[2:3], v[6:9], off nt
	v_mov_b32_e32 v2, v12
	s_nop 1
	v_permlane16_swap_b32_e32 v12, v2
	v_add_f32_e32 v2, v12, v2
	v_mov_b32_e32 v3, v2
	s_nop 1
	v_permlane32_swap_b32_e32 v2, v3
	v_add_f32_e32 v167, v2, v3
	v_mbcnt_lo_u32_b32 v200, -1, 0
	v_mbcnt_hi_u32_b32 v200, -1, v200
	v_lshrrev_b32_e32 v201, 4, v200
	v_cmp_eq_u32_e64 s[100:101], 1, v201
	s_nop 1
	v_cndmask_b32_e64 v212, v164, v165, s[100:101]
	v_cmp_eq_u32_e64 s[100:101], 2, v201
	s_nop 1
	v_cndmask_b32_e64 v212, v212, v166, s[100:101]
	v_cmp_eq_u32_e64 s[100:101], 3, v201
	s_nop 1
	v_cndmask_b32_e64 v212, v212, v167, s[100:101]
	s_nop 1
	s_add_u32 s100, s82, s46
	s_addc_u32 s101, s83, s47
	v_or_b32_e32 v201, s44, v174
	v_lshlrev_b32_e32 v201, 2, v201
	v_and_b32_e32 v200, 48, v200
	v_lshl_add_u32 v201, v200, 2, v201
	global_store_dword v201, v212, s[100:101] offset:512
	s_andn2_b64 vcc, exec, s[36:37]
	s_mov_b64 s[36:37], -1
	s_cbranch_vccnz .LBB0_745
	s_andn2_b64 vcc, exec, s[18:19]
	s_cbranch_vccnz .LBB0_744
	s_barrier
	s_branch .LBB0_744

; #define PG8_LAS __attribute__((address_space(3)))
;     __device__ __forceinline__ void operator()(const f32x4 (&acc)[2][2][4][2], const Unit& u, int wr, int wc, int fr, int fq, PG8_LAS unsigned char* stg) const {
;         const int lane = fq * 16 + fr;
;         const size_t colw = (size_t)u.pn * BM + wc * 64;
;         const int rowb = u.pm * BM + wr * 64;
;         PG8_LAS unsigned char* st = stg + fr * 144 + fq * 16;
; #pragma unroll
;         for (int ai = 0; ai < 2; ++ai) {
;         asm volatile("" ::: "memory");
;         u32x4 xin[4][2];
; #pragma unroll
;         for (int m = 0; m < 4; ++m)
; #pragma unroll
;             for (int i = 0; i < 2; ++i) { const int c = lane + 64 * i; xin[m][i] = *(const u32x4*)(xb + (size_t)(rowb + ai * HALF + m * 16 + (c >> 3)) * 1024 + colw + (c & 7) * 8); }
; #pragma unroll
;         for (int m = 0; m < 4; ++m) {
;             const int row = rowb + ai * HALF + m * 16 + fr;
; #pragma unroll
;             for (int i = 0; i < 2; ++i) { const int c = lane + 64 * i; *(PG8_LAS u32x4*)(stg + (c >> 3) * 144 + (c & 7) * 16) = xin[m][i]; }
;             float ss = 0.f;
; #pragma unroll
;             for (int bj = 0; bj < 2; ++bj) {
;                 const u32x4 xo = *(const PG8_LAS u32x4*)(st + bj * 64);
;                 float v[8];
; #pragma unroll
;                 for (int i = 0; i < 4; ++i) { v[2 * i] = __uint_as_float(xo[i] << 16) + acc[ai][bj][m][i >> 1][(2 * i) & 3]; v[2 * i + 1] = __uint_as_float(xo[i] & 0xffff0000u) + acc[ai][bj][m][i >> 1][(2 * i + 1) & 3]; }
;                 u32x4 w; w.x = cvt_pk_bf16(v[0], v[1]); w.y = cvt_pk_bf16(v[2], v[3]); w.z = cvt_pk_bf16(v[4], v[5]); w.w = cvt_pk_bf16(v[6], v[7]);
;                 *(PG8_LAS u32x4*)(st + bj * 64) = w;
;                 ss += ((v[0] * v[0] + v[1] * v[1]) + (v[2] * v[2] + v[3] * v[3])) + ((v[4] * v[4] + v[5] * v[5]) + (v[6] * v[6] + v[7] * v[7]));
;             }
; #pragma unroll
;             for (int i = 0; i < 2; ++i) { const int c = lane + 64 * i; const u32x4 w = *(const PG8_LAS u32x4*)(stg + (c >> 3) * 144 + (c & 7) * 16);
;                 *(u32x4*)(xo_ + (size_t)(row - fr + (c >> 3)) * 1024 + colw + (c & 7) * 8) = w; }
;             ss = sum_x16(ss); ss = sum_x32(ss);
;             if (fq == 0) po_[(size_t)(u.pn * 4 + wc) * 65536 + row] = ss;
.LBB0_926:
	s_ashr_i32 s45, s44, 31
	s_lshl_b32 s14, s14, 8
	s_lshl_b64 s[16:17], s[44:45], 8
	s_add_i32 s42, s14, s10
	s_or_b64 s[16:17], s[16:17], s[74:75]
	v_or_b32_e32 v130, s42, v206
	s_lshl_b64 s[46:47], s[16:17], 1
	v_ashrrev_i32_e32 v131, 31, v130
	v_lshl_add_u64 v[182:183], v[176:177], 0, s[46:47]
	v_lshlrev_b64 v[198:199], 11, v[130:131]
	v_lshl_add_u64 v[130:131], v[182:183], 0, v[198:199]
	global_load_dwordx4 v[154:157], v[130:131], off nt
	v_or_b32_e32 v130, s42, v207
	v_ashrrev_i32_e32 v131, 31, v130
	v_lshlrev_b64 v[196:197], 11, v[130:131]
	v_lshl_add_u64 v[130:131], v[182:183], 0, v[196:197]
	global_load_dwordx4 v[160:163], v[130:131], off nt
	s_lshl_b32 s14, s44, 2
	s_or_b32 s14, s14, s9
	s_ashr_i32 s15, s14, 31
	s_lshl_b64 s[44:45], s[14:15], 18
	s_or_b32 s14, s42, 16
	v_or_b32_e32 v130, s14, v206
	v_ashrrev_i32_e32 v131, 31, v130
	v_lshlrev_b64 v[194:195], 11, v[130:131]
	v_lshl_add_u64 v[130:131], v[182:183], 0, v[194:195]
	global_load_dwordx4 v[146:149], v[130:131], off nt
	v_or_b32_e32 v130, s14, v207
	v_ashrrev_i32_e32 v131, 31, v130
	v_lshlrev_b64 v[192:193], 11, v[130:131]
	v_lshl_add_u64 v[130:131], v[182:183], 0, v[192:193]
	s_or_b32 s14, s42, 32
	global_load_dwordx4 v[150:153], v[130:131], off nt
	v_or_b32_e32 v130, s14, v206
	v_ashrrev_i32_e32 v131, 31, v130
	v_lshlrev_b64 v[188:189], 11, v[130:131]
	v_lshl_add_u64 v[130:131], v[182:183], 0, v[188:189]
	global_load_dwordx4 v[134:137], v[130:131], off nt
	v_or_b32_e32 v130, s14, v207
	v_ashrrev_i32_e32 v131, 31, v130
	v_lshlrev_b64 v[186:187], 11, v[130:131]
	v_lshl_add_u64 v[130:131], v[182:183], 0, v[186:187]
	s_or_b32 s14, s42, 48
	global_load_dwordx4 v[138:141], v[130:131], off nt
	v_or_b32_e32 v130, s14, v206
	v_or_b32_e32 v142, s14, v207
	v_ashrrev_i32_e32 v131, 31, v130
	v_ashrrev_i32_e32 v143, 31, v142
	v_lshlrev_b64 v[184:185], 11, v[130:131]
	v_lshlrev_b64 v[190:191], 11, v[142:143]
	v_lshl_add_u64 v[130:131], v[182:183], 0, v[184:185]
	v_lshl_add_u64 v[142:143], v[182:183], 0, v[190:191]
	global_load_dwordx4 v[130:133], v[130:131], off nt
	s_nop 0
	global_load_dwordx4 v[142:145], v[142:143], off nt
	s_waitcnt vmcnt(0)
	ds_write_b128 v209, v[154:157]
	ds_write_b128 v209, v[160:163] offset:1152
	ds_read_b128 v[154:157], v210
	s_waitcnt lgkmcnt(0)
	v_lshlrev_b32_e32 v160, 16, v154
	v_and_b32_e32 v154, 0xffff0000, v154
	v_add_f32_e32 v127, v127, v154
	v_lshlrev_b32_e32 v154, 16, v155
	v_add_f32_e32 v128, v128, v154
	v_and_b32_e32 v154, 0xffff0000, v155
	v_add_f32_e32 v129, v129, v154
	v_lshlrev_b32_e32 v154, 16, v156
	v_add_f32_e32 v154, v122, v154
	v_and_b32_e32 v122, 0xffff0000, v156
	v_add_f32_e32 v155, v123, v122
	v_lshlrev_b32_e32 v122, 16, v157
	v_add_f32_e32 v156, v124, v122
	v_and_b32_e32 v122, 0xffff0000, v157
	v_add_f32_e32 v126, v126, v160
	v_add_f32_e32 v157, v125, v122
	v_cvt_pk_bf16_f32 v122, v126, v127
	v_cvt_pk_bf16_f32 v123, v128, v129
	v_cvt_pk_bf16_f32 v124, v154, v155
	v_cvt_pk_bf16_f32 v125, v156, v157
	ds_write_b128 v210, v[122:125]
	v_mul_f32_e32 v122, v127, v127
	v_mul_f32_e32 v123, v129, v129
	v_fmac_f32_e32 v122, v126, v126
	v_fmac_f32_e32 v123, v128, v128
	v_add_f32_e32 v122, v122, v123
	v_mul_f32_e32 v123, v155, v155
	v_mul_f32_e32 v124, v157, v157
	v_fmac_f32_e32 v123, v154, v154
	v_fmac_f32_e32 v124, v156, v156
	v_add_f32_e32 v123, v123, v124
	v_add_f32_e32 v126, v122, v123
	ds_read_b128 v[122:125], v210 offset:64
	s_waitcnt lgkmcnt(0)
	v_lshlrev_b32_e32 v127, 16, v122
	v_and_b32_e32 v122, 0xffff0000, v122
	v_add_f32_e32 v119, v119, v122
	v_lshlrev_b32_e32 v122, 16, v123
	v_add_f32_e32 v120, v120, v122
	v_and_b32_e32 v122, 0xffff0000, v123
	v_add_f32_e32 v121, v121, v122
	v_lshlrev_b32_e32 v122, 16, v124
	v_add_f32_e32 v122, v114, v122
	v_and_b32_e32 v114, 0xffff0000, v124
	v_add_f32_e32 v123, v115, v114
	v_lshlrev_b32_e32 v114, 16, v125
	v_add_f32_e32 v124, v116, v114
	v_and_b32_e32 v114, 0xffff0000, v125
	v_add_f32_e32 v118, v118, v127
	v_add_f32_e32 v125, v117, v114
	v_cvt_pk_bf16_f32 v114, v118, v119
	v_cvt_pk_bf16_f32 v115, v120, v121
	v_cvt_pk_bf16_f32 v116, v122, v123
	v_cvt_pk_bf16_f32 v117, v124, v125
	ds_write_b128 v210, v[114:117] offset:64
	v_mul_f32_e32 v114, v119, v119
	v_mul_f32_e32 v115, v121, v121
	v_fmac_f32_e32 v114, v118, v118
	v_fmac_f32_e32 v115, v120, v120
	v_add_f32_e32 v114, v114, v115
	v_mul_f32_e32 v115, v123, v123
	v_mul_f32_e32 v116, v125, v125
	v_fmac_f32_e32 v115, v122, v122
	v_fmac_f32_e32 v116, v124, v124
	v_add_f32_e32 v115, v115, v116
	v_add_f32_e32 v114, v114, v115
	v_add_f32_e32 v120, v126, v114
	ds_read_b128 v[114:117], v211
	v_lshl_add_u64 v[118:119], s[76:77], 0, v[198:199]
	v_lshl_add_u64 v[118:119], v[118:119], 0, s[46:47]
	v_lshl_add_u64 v[118:119], v[118:119], 0, v[0:1]
	s_waitcnt lgkmcnt(0)
	global_store_dwordx4 v[118:119], v[114:117], off nt
	ds_read_b128 v[114:117], v211 offset:1152
	v_lshl_add_u64 v[118:119], s[76:77], 0, v[196:197]
	v_lshl_add_u64 v[118:119], v[118:119], 0, s[46:47]
	v_lshl_add_u64 v[118:119], v[118:119], 0, v[0:1]
	s_waitcnt lgkmcnt(0)
	global_store_dwordx4 v[118:119], v[114:117], off nt
	s_nop 1
	v_mov_b32_e32 v114, v120
	s_nop 1
	v_permlane16_swap_b32_e32 v120, v114
	v_add_f32_e32 v114, v120, v114
	v_mov_b32_e32 v115, v114
	s_nop 1
	v_permlane32_swap_b32_e32 v114, v115
	v_add_f32_e32 v164, v114, v115
	ds_write_b128 v209, v[146:149]
	ds_write_b128 v209, v[150:153] offset:1152
	ds_read_b128 v[114:117], v210
	s_waitcnt lgkmcnt(0)
; #define PG8_LAS __attribute__((address_space(3)))
; __device__ __forceinline__ unsigned cvt_pk_bf16(float lo, float hi) { unsigned r; asm volatile("v_cvt_pk_bf16_f32 %0, %1, %2" : "=v"(r) : "v"(lo), "v"(hi)); return r; }
; __device__ __forceinline__ float sum_x16(float s) { auto r = __builtin_amdgcn_permlane16_swap(__float_as_uint(s), __float_as_uint(s), false, false); return __uint_as_float(r[0]) + __uint_as_float(r[1]); }
; __device__ __forceinline__ float sum_x32(float s) { auto r = __builtin_amdgcn_permlane32_swap(__float_as_uint(s), __float_as_uint(s), false, false); return __uint_as_float(r[0]) + __uint_as_float(r[1]); }
;     __device__ __forceinline__ void operator()(const f32x4 (&acc)[2][2][4][2], const Unit& u, int wr, int wc, int fr, int fq, PG8_LAS unsigned char* stg) const {
;     ...
;         for (int m = 0; m < 4; ++m) {
;             const int row = rowb + ai * HALF + m * 16 + fr;
; #pragma unroll
;             for (int i = 0; i < 2; ++i) { const int c = lane + 64 * i; *(PG8_LAS u32x4*)(stg + (c >> 3) * 144 + (c & 7) * 16) = xin[m][i]; }
;             float ss = 0.f;
; #pragma unroll
;             for (int bj = 0; bj < 2; ++bj) {
;                 const u32x4 xo = *(const PG8_LAS u32x4*)(st + bj * 64);
;                 float v[8];
; #pragma unroll
;                 for (int i = 0; i < 4; ++i) { v[2 * i] = __uint_as_float(xo[i] << 16) + acc[ai][bj][m][i >> 1][(2 * i) & 3]; v[2 * i + 1] = __uint_as_float(xo[i] & 0xffff0000u) + acc[ai][bj][m][i >> 1][(2 * i + 1) & 3]; }
;                 u32x4 w; w.x = cvt_pk_bf16(v[0], v[1]); w.y = cvt_pk_bf16(v[2], v[3]); w.z = cvt_pk_bf16(v[4], v[5]); w.w = cvt_pk_bf16(v[6], v[7]);
;                 *(PG8_LAS u32x4*)(st + bj * 64) = w;
;                 ss += ((v[0] * v[0] + v[1] * v[1]) + (v[2] * v[2] + v[3] * v[3])) + ((v[4] * v[4] + v[5] * v[5]) + (v[6] * v[6] + v[7] * v[7]));
;             }
; #pragma unroll
;             for (int i = 0; i < 2; ++i) { const int c = lane + 64 * i; const u32x4 w = *(const PG8_LAS u32x4*)(stg + (c >> 3) * 144 + (c & 7) * 16);
;                 *(u32x4*)(xo_ + (size_t)(row - fr + (c >> 3)) * 1024 + colw + (c & 7) * 8) = w; }
;             ss = sum_x16(ss); ss = sum_x32(ss);
	v_lshlrev_b32_e32 v118, 16, v114
	v_and_b32_e32 v114, 0xffff0000, v114
	v_add_f32_e32 v111, v111, v114
	v_and_b32_e32 v114, 0xffff0000, v115
	v_add_f32_e32 v113, v113, v114
	v_lshlrev_b32_e32 v114, 16, v116
	v_add_f32_e32 v114, v106, v114
	v_and_b32_e32 v106, 0xffff0000, v116
	v_lshlrev_b32_e32 v119, 16, v115
	v_add_f32_e32 v115, v107, v106
	v_lshlrev_b32_e32 v106, 16, v117
	v_add_f32_e32 v116, v108, v106
	v_and_b32_e32 v106, 0xffff0000, v117
	v_add_f32_e32 v110, v110, v118
	v_add_f32_e32 v112, v112, v119
	v_add_f32_e32 v117, v109, v106
	v_cvt_pk_bf16_f32 v106, v110, v111
	v_cvt_pk_bf16_f32 v107, v112, v113
	v_cvt_pk_bf16_f32 v108, v114, v115
	v_cvt_pk_bf16_f32 v109, v116, v117
	ds_write_b128 v210, v[106:109]
	v_mul_f32_e32 v106, v111, v111
	v_mul_f32_e32 v107, v113, v113
	v_fmac_f32_e32 v106, v110, v110
	v_fmac_f32_e32 v107, v112, v112
	v_add_f32_e32 v110, v106, v107
	ds_read_b128 v[106:109], v210 offset:64
	v_mul_f32_e32 v111, v115, v115
	v_mul_f32_e32 v112, v117, v117
	v_fmac_f32_e32 v111, v114, v114
	v_fmac_f32_e32 v112, v116, v116
	v_add_f32_e32 v111, v111, v112
	v_add_f32_e32 v110, v110, v111
	s_waitcnt lgkmcnt(0)
	v_lshlrev_b32_e32 v111, 16, v106
	v_and_b32_e32 v106, 0xffff0000, v106
	v_add_f32_e32 v103, v103, v106
	v_lshlrev_b32_e32 v106, 16, v107
	v_add_f32_e32 v104, v104, v106
	v_and_b32_e32 v106, 0xffff0000, v107
	v_add_f32_e32 v105, v105, v106
	v_lshlrev_b32_e32 v106, 16, v108
	v_add_f32_e32 v106, v98, v106
	v_and_b32_e32 v98, 0xffff0000, v108
	v_add_f32_e32 v107, v99, v98
	v_lshlrev_b32_e32 v98, 16, v109
	v_add_f32_e32 v108, v100, v98
	v_and_b32_e32 v98, 0xffff0000, v109
	v_add_f32_e32 v102, v102, v111
	v_add_f32_e32 v109, v101, v98
	v_cvt_pk_bf16_f32 v98, v102, v103
	v_cvt_pk_bf16_f32 v99, v104, v105
	v_cvt_pk_bf16_f32 v100, v106, v107
	v_cvt_pk_bf16_f32 v101, v108, v109
	ds_write_b128 v210, v[98:101] offset:64
	v_mul_f32_e32 v98, v103, v103
	v_mul_f32_e32 v99, v105, v105
	v_fmac_f32_e32 v98, v102, v102
	v_fmac_f32_e32 v99, v104, v104
	v_add_f32_e32 v98, v98, v99
	v_mul_f32_e32 v99, v107, v107
	v_mul_f32_e32 v100, v109, v109
	v_fmac_f32_e32 v99, v106, v106
	v_fmac_f32_e32 v100, v108, v108
	v_add_f32_e32 v99, v99, v100
	v_add_f32_e32 v98, v98, v99
	v_add_f32_e32 v108, v110, v98
	ds_read_b128 v[98:101], v211
	v_lshl_add_u64 v[102:103], s[76:77], 0, v[194:195]
	v_lshl_add_u64 v[102:103], v[102:103], 0, s[46:47]
	v_lshl_add_u64 v[106:107], v[102:103], 0, v[0:1]
	ds_read_b128 v[102:105], v211 offset:1152
	s_waitcnt lgkmcnt(1)
	global_store_dwordx4 v[106:107], v[98:101], off nt
	s_nop 1
	v_lshl_add_u64 v[98:99], s[76:77], 0, v[192:193]
	v_lshl_add_u64 v[98:99], v[98:99], 0, s[46:47]
	v_lshl_add_u64 v[98:99], v[98:99], 0, v[0:1]
	s_waitcnt lgkmcnt(0)
	global_store_dwordx4 v[98:99], v[102:105], off nt
	v_mov_b32_e32 v98, v108
	s_nop 1
	v_permlane16_swap_b32_e32 v108, v98
	v_add_f32_e32 v98, v108, v98
	v_mov_b32_e32 v99, v98
	s_nop 1
	v_permlane32_swap_b32_e32 v98, v99
	v_add_f32_e32 v165, v98, v99
	ds_write_b128 v209, v[134:137]
	ds_write_b128 v209, v[138:141] offset:1152
	ds_read_b128 v[98:101], v210
	s_waitcnt lgkmcnt(0)
	v_lshlrev_b32_e32 v102, 16, v98
	v_and_b32_e32 v98, 0xffff0000, v98
	v_add_f32_e32 v95, v95, v98
	v_and_b32_e32 v98, 0xffff0000, v99
	v_add_f32_e32 v97, v97, v98
	v_lshlrev_b32_e32 v98, 16, v100
	v_add_f32_e32 v98, v90, v98
	v_and_b32_e32 v90, 0xffff0000, v100
	v_lshlrev_b32_e32 v103, 16, v99
	v_add_f32_e32 v99, v91, v90
	v_lshlrev_b32_e32 v90, 16, v101
	v_add_f32_e32 v100, v92, v90
	v_and_b32_e32 v90, 0xffff0000, v101
	v_add_f32_e32 v94, v94, v102
	v_add_f32_e32 v96, v96, v103
	v_add_f32_e32 v101, v93, v90
	v_cvt_pk_bf16_f32 v90, v94, v95
	v_cvt_pk_bf16_f32 v91, v96, v97
	v_cvt_pk_bf16_f32 v92, v98, v99
	v_cvt_pk_bf16_f32 v93, v100, v101
	ds_write_b128 v210, v[90:93]
	v_mul_f32_e32 v90, v95, v95
	v_mul_f32_e32 v91, v97, v97
	v_fmac_f32_e32 v90, v94, v94
	v_fmac_f32_e32 v91, v96, v96
	v_add_f32_e32 v94, v90, v91
	ds_read_b128 v[90:93], v210 offset:64
	v_mul_f32_e32 v95, v99, v99
	v_mul_f32_e32 v96, v101, v101
	v_fmac_f32_e32 v95, v98, v98
	v_fmac_f32_e32 v96, v100, v100
	v_add_f32_e32 v95, v95, v96
	v_add_f32_e32 v94, v94, v95
	s_waitcnt lgkmcnt(0)
	v_lshlrev_b32_e32 v95, 16, v90
	v_and_b32_e32 v90, 0xffff0000, v90
	v_add_f32_e32 v87, v87, v90
	v_lshlrev_b32_e32 v90, 16, v91
	v_add_f32_e32 v88, v88, v90
	v_and_b32_e32 v90, 0xffff0000, v91
	v_add_f32_e32 v89, v89, v90
	v_lshlrev_b32_e32 v90, 16, v92
	v_add_f32_e32 v90, v82, v90
	v_and_b32_e32 v82, 0xffff0000, v92
	v_add_f32_e32 v91, v83, v82
	v_lshlrev_b32_e32 v82, 16, v93
	v_add_f32_e32 v92, v84, v82
	v_and_b32_e32 v82, 0xffff0000, v93
	v_add_f32_e32 v86, v86, v95
	v_add_f32_e32 v93, v85, v82
	v_cvt_pk_bf16_f32 v82, v86, v87
	v_cvt_pk_bf16_f32 v83, v88, v89
	v_cvt_pk_bf16_f32 v84, v90, v91
	v_cvt_pk_bf16_f32 v85, v92, v93
	ds_write_b128 v210, v[82:85] offset:64
	v_mul_f32_e32 v82, v87, v87
	v_mul_f32_e32 v83, v89, v89
	v_fmac_f32_e32 v82, v86, v86
	v_fmac_f32_e32 v83, v88, v88
	v_add_f32_e32 v82, v82, v83
	v_mul_f32_e32 v83, v91, v91
	v_mul_f32_e32 v84, v93, v93
	v_fmac_f32_e32 v83, v90, v90
	v_fmac_f32_e32 v84, v92, v92
	v_add_f32_e32 v83, v83, v84
	v_add_f32_e32 v82, v82, v83
	v_add_f32_e32 v92, v94, v82
	ds_read_b128 v[82:85], v211
	v_lshl_add_u64 v[86:87], s[76:77], 0, v[188:189]
	v_lshl_add_u64 v[86:87], v[86:87], 0, s[46:47]
	v_lshl_add_u64 v[90:91], v[86:87], 0, v[0:1]
	ds_read_b128 v[86:89], v211 offset:1152
	s_waitcnt lgkmcnt(1)
	global_store_dwordx4 v[90:91], v[82:85], off nt
	s_nop 1
	v_lshl_add_u64 v[82:83], s[76:77], 0, v[186:187]
	v_lshl_add_u64 v[82:83], v[82:83], 0, s[46:47]
	v_lshl_add_u64 v[82:83], v[82:83], 0, v[0:1]
	s_waitcnt lgkmcnt(0)
; #define PG8_LAS __attribute__((address_space(3)))
; __device__ __forceinline__ unsigned cvt_pk_bf16(float lo, float hi) { unsigned r; asm volatile("v_cvt_pk_bf16_f32 %0, %1, %2" : "=v"(r) : "v"(lo), "v"(hi)); return r; }
; __device__ __forceinline__ float sum_x16(float s) { auto r = __builtin_amdgcn_permlane16_swap(__float_as_uint(s), __float_as_uint(s), false, false); return __uint_as_float(r[0]) + __uint_as_float(r[1]); }
;     __device__ __forceinline__ void operator()(const f32x4 (&acc)[2][2][4][2], const Unit& u, int wr, int wc, int fr, int fq, PG8_LAS unsigned char* stg) const {
;     ...
;             for (int i = 0; i < 2; ++i) { const int c = lane + 64 * i; xin[m][i] = *(const u32x4*)(xb + (size_t)(rowb + ai * HALF + m * 16 + (c >> 3)) * 1024 + colw + (c & 7) * 8); }
; #pragma unroll
;         for (int m = 0; m < 4; ++m) {
;             const int row = rowb + ai * HALF + m * 16 + fr;
; #pragma unroll
;             for (int i = 0; i < 2; ++i) { const int c = lane + 64 * i; *(PG8_LAS u32x4*)(stg + (c >> 3) * 144 + (c & 7) * 16) = xin[m][i]; }
;             float ss = 0.f;
; #pragma unroll
;             for (int bj = 0; bj < 2; ++bj) {
;                 const u32x4 xo = *(const PG8_LAS u32x4*)(st + bj * 64);
;                 float v[8];
; #pragma unroll
;                 for (int i = 0; i < 4; ++i) { v[2 * i] = __uint_as_float(xo[i] << 16) + acc[ai][bj][m][i >> 1][(2 * i) & 3]; v[2 * i + 1] = __uint_as_float(xo[i] & 0xffff0000u) + acc[ai][bj][m][i >> 1][(2 * i + 1) & 3]; }
;                 u32x4 w; w.x = cvt_pk_bf16(v[0], v[1]); w.y = cvt_pk_bf16(v[2], v[3]); w.z = cvt_pk_bf16(v[4], v[5]); w.w = cvt_pk_bf16(v[6], v[7]);
;                 *(PG8_LAS u32x4*)(st + bj * 64) = w;
;                 ss += ((v[0] * v[0] + v[1] * v[1]) + (v[2] * v[2] + v[3] * v[3])) + ((v[4] * v[4] + v[5] * v[5]) + (v[6] * v[6] + v[7] * v[7]));
;             }
; #pragma unroll
;             for (int i = 0; i < 2; ++i) { const int c = lane + 64 * i; const u32x4 w = *(const PG8_LAS u32x4*)(stg + (c >> 3) * 144 + (c & 7) * 16);
;                 *(u32x4*)(xo_ + (size_t)(row - fr + (c >> 3)) * 1024 + colw + (c & 7) * 8) = w; }
;             ss = sum_x16(ss); ss = sum_x32(ss);
;             if (fq == 0) po_[(size_t)(u.pn * 4 + wc) * 65536 + row] = ss;
	global_store_dwordx4 v[82:83], v[86:89], off nt
	v_mov_b32_e32 v82, v92
	s_nop 1
	v_permlane16_swap_b32_e32 v92, v82
	v_add_f32_e32 v82, v92, v82
	v_mov_b32_e32 v83, v82
	s_nop 1
	v_permlane32_swap_b32_e32 v82, v83
	v_add_f32_e32 v166, v82, v83
	ds_write_b128 v209, v[130:133]
	ds_write_b128 v209, v[142:145] offset:1152
	ds_read_b128 v[82:85], v210
	s_waitcnt lgkmcnt(0)
	v_lshlrev_b32_e32 v86, 16, v82
	v_and_b32_e32 v82, 0xffff0000, v82
	v_add_f32_e32 v79, v79, v82
	v_and_b32_e32 v82, 0xffff0000, v83
	v_add_f32_e32 v81, v81, v82
	v_lshlrev_b32_e32 v82, 16, v84
	v_add_f32_e32 v82, v74, v82
	v_and_b32_e32 v74, 0xffff0000, v84
	v_lshlrev_b32_e32 v87, 16, v83
	v_add_f32_e32 v83, v75, v74
	v_lshlrev_b32_e32 v74, 16, v85
	v_add_f32_e32 v84, v76, v74
	v_and_b32_e32 v74, 0xffff0000, v85
	v_add_f32_e32 v78, v78, v86
	v_add_f32_e32 v80, v80, v87
	v_add_f32_e32 v85, v77, v74
	v_cvt_pk_bf16_f32 v74, v78, v79
	v_cvt_pk_bf16_f32 v75, v80, v81
	v_cvt_pk_bf16_f32 v76, v82, v83
	v_cvt_pk_bf16_f32 v77, v84, v85
	ds_write_b128 v210, v[74:77]
	v_mul_f32_e32 v74, v79, v79
	v_mul_f32_e32 v75, v81, v81
	v_fmac_f32_e32 v74, v78, v78
	v_fmac_f32_e32 v75, v80, v80
	v_add_f32_e32 v78, v74, v75
	ds_read_b128 v[74:77], v210 offset:64
	v_mul_f32_e32 v79, v83, v83
	v_mul_f32_e32 v80, v85, v85
	v_fmac_f32_e32 v79, v82, v82
	v_fmac_f32_e32 v80, v84, v84
	v_add_f32_e32 v79, v79, v80
	v_add_f32_e32 v78, v78, v79
	s_waitcnt lgkmcnt(0)
	v_lshlrev_b32_e32 v79, 16, v74
	v_and_b32_e32 v74, 0xffff0000, v74
	v_add_f32_e32 v71, v71, v74
	v_lshlrev_b32_e32 v74, 16, v75
	v_add_f32_e32 v72, v72, v74
	v_and_b32_e32 v74, 0xffff0000, v75
	v_add_f32_e32 v73, v73, v74
	v_lshlrev_b32_e32 v74, 16, v76
	v_add_f32_e32 v74, v66, v74
	v_and_b32_e32 v66, 0xffff0000, v76
	v_add_f32_e32 v75, v67, v66
	v_lshlrev_b32_e32 v66, 16, v77
	v_add_f32_e32 v76, v68, v66
	v_and_b32_e32 v66, 0xffff0000, v77
	v_add_f32_e32 v70, v70, v79
	v_add_f32_e32 v77, v69, v66
	v_cvt_pk_bf16_f32 v66, v70, v71
	v_cvt_pk_bf16_f32 v67, v72, v73
	v_cvt_pk_bf16_f32 v68, v74, v75
	v_cvt_pk_bf16_f32 v69, v76, v77
	ds_write_b128 v210, v[66:69] offset:64
	v_mul_f32_e32 v66, v71, v71
	v_mul_f32_e32 v67, v73, v73
	v_fmac_f32_e32 v66, v70, v70
	v_fmac_f32_e32 v67, v72, v72
	v_add_f32_e32 v66, v66, v67
	v_mul_f32_e32 v67, v75, v75
	v_mul_f32_e32 v68, v77, v77
	v_fmac_f32_e32 v67, v74, v74
	v_fmac_f32_e32 v68, v76, v76
	v_add_f32_e32 v67, v67, v68
	v_add_f32_e32 v66, v66, v67
	v_add_f32_e32 v76, v78, v66
	ds_read_b128 v[66:69], v211
	v_lshl_add_u64 v[70:71], s[76:77], 0, v[184:185]
	v_lshl_add_u64 v[70:71], v[70:71], 0, s[46:47]
	v_lshl_add_u64 v[74:75], v[70:71], 0, v[0:1]
	ds_read_b128 v[70:73], v211 offset:1152
	s_waitcnt lgkmcnt(1)
	global_store_dwordx4 v[74:75], v[66:69], off nt
	s_nop 1
	v_lshl_add_u64 v[66:67], s[76:77], 0, v[190:191]
	v_lshl_add_u64 v[66:67], v[66:67], 0, s[46:47]
	v_lshl_add_u64 v[66:67], v[66:67], 0, v[0:1]
	s_waitcnt lgkmcnt(0)
	global_store_dwordx4 v[66:67], v[70:73], off nt
	v_mov_b32_e32 v66, v76
	s_nop 1
	v_permlane16_swap_b32_e32 v76, v66
	v_add_f32_e32 v66, v76, v66
	v_mov_b32_e32 v67, v66
	s_nop 1
	v_permlane32_swap_b32_e32 v66, v67
	v_add_f32_e32 v167, v66, v67
	v_mbcnt_lo_u32_b32 v200, -1, 0
	v_mbcnt_hi_u32_b32 v200, -1, v200
	v_lshrrev_b32_e32 v201, 4, v200
	v_cmp_eq_u32_e64 s[100:101], 1, v201
	s_nop 1
	v_cndmask_b32_e64 v212, v164, v165, s[100:101]
	v_cmp_eq_u32_e64 s[100:101], 2, v201
	s_nop 1
	v_cndmask_b32_e64 v212, v212, v166, s[100:101]
	v_cmp_eq_u32_e64 s[100:101], 3, v201
	s_nop 1
	v_cndmask_b32_e64 v212, v212, v167, s[100:101]
	s_nop 1
	s_add_u32 s100, s82, s44
	s_addc_u32 s101, s83, s45
	v_or_b32_e32 v201, s42, v174
	v_lshlrev_b32_e32 v201, 2, v201
	v_and_b32_e32 v200, 48, v200
	v_lshl_add_u32 v201, v200, 2, v201
	global_store_dword v201, v212, s[100:101] offset:0
	s_add_i32 s14, s42, 0x80
	v_or_b32_e32 v66, s14, v206
	v_ashrrev_i32_e32 v67, 31, v66
	v_lshlrev_b64 v[104:105], 11, v[66:67]
	v_lshl_add_u64 v[66:67], v[182:183], 0, v[104:105]
	global_load_dwordx4 v[106:109], v[66:67], off nt
	v_or_b32_e32 v66, s14, v207
	v_ashrrev_i32_e32 v67, 31, v66
	v_lshlrev_b64 v[102:103], 11, v[66:67]
	v_lshl_add_u64 v[66:67], v[182:183], 0, v[102:103]
	global_load_dwordx4 v[110:113], v[66:67], off nt
	s_add_i32 s14, s42, 0x90
	v_or_b32_e32 v66, s14, v206
	v_ashrrev_i32_e32 v67, 31, v66
	v_lshlrev_b64 v[100:101], 11, v[66:67]
	v_lshl_add_u64 v[66:67], v[182:183], 0, v[100:101]
	global_load_dwordx4 v[82:85], v[66:67], off nt
	v_or_b32_e32 v66, s14, v207
	v_ashrrev_i32_e32 v67, 31, v66
	v_lshlrev_b64 v[98:99], 11, v[66:67]
	v_lshl_add_u64 v[66:67], v[182:183], 0, v[98:99]
	s_add_i32 s14, s42, 0xa0
	global_load_dwordx4 v[86:89], v[66:67], off nt
	v_or_b32_e32 v66, s14, v206
	v_ashrrev_i32_e32 v67, 31, v66
	v_lshlrev_b64 v[94:95], 11, v[66:67]
	v_lshl_add_u64 v[66:67], v[182:183], 0, v[94:95]
	global_load_dwordx4 v[70:73], v[66:67], off nt
	v_or_b32_e32 v66, s14, v207
	v_ashrrev_i32_e32 v67, 31, v66
	v_lshlrev_b64 v[92:93], 11, v[66:67]
	v_lshl_add_u64 v[66:67], v[182:183], 0, v[92:93]
	s_add_i32 s14, s42, 0xb0
	global_load_dwordx4 v[74:77], v[66:67], off nt
	v_or_b32_e32 v66, s14, v206
	v_or_b32_e32 v78, s14, v207
	v_ashrrev_i32_e32 v67, 31, v66
	v_ashrrev_i32_e32 v79, 31, v78
	v_lshlrev_b64 v[90:91], 11, v[66:67]
	v_lshlrev_b64 v[96:97], 11, v[78:79]
	v_lshl_add_u64 v[66:67], v[182:183], 0, v[90:91]
	v_lshl_add_u64 v[78:79], v[182:183], 0, v[96:97]
	global_load_dwordx4 v[66:69], v[66:67], off nt
	s_nop 0
	global_load_dwordx4 v[78:81], v[78:79], off nt
	s_waitcnt vmcnt(7)
	ds_write_b128 v209, v[106:109]
	s_waitcnt vmcnt(6)
	ds_write_b128 v209, v[110:113] offset:1152
	ds_read_b128 v[106:109], v210
	s_waitcnt lgkmcnt(0)
; #define PG8_LAS __attribute__((address_space(3)))
; __device__ __forceinline__ unsigned cvt_pk_bf16(float lo, float hi) { unsigned r; asm volatile("v_cvt_pk_bf16_f32 %0, %1, %2" : "=v"(r) : "v"(lo), "v"(hi)); return r; }
; __device__ __forceinline__ float sum_x16(float s) { auto r = __builtin_amdgcn_permlane16_swap(__float_as_uint(s), __float_as_uint(s), false, false); return __uint_as_float(r[0]) + __uint_as_float(r[1]); }
; __device__ __forceinline__ float sum_x32(float s) { auto r = __builtin_amdgcn_permlane32_swap(__float_as_uint(s), __float_as_uint(s), false, false); return __uint_as_float(r[0]) + __uint_as_float(r[1]); }
;     __device__ __forceinline__ void operator()(const f32x4 (&acc)[2][2][4][2], const Unit& u, int wr, int wc, int fr, int fq, PG8_LAS unsigned char* stg) const {
;     ...
;         for (int m = 0; m < 4; ++m) {
;             const int row = rowb + ai * HALF + m * 16 + fr;
; #pragma unroll
;             for (int i = 0; i < 2; ++i) { const int c = lane + 64 * i; *(PG8_LAS u32x4*)(stg + (c >> 3) * 144 + (c & 7) * 16) = xin[m][i]; }
;             float ss = 0.f;
; #pragma unroll
;             for (int bj = 0; bj < 2; ++bj) {
;                 const u32x4 xo = *(const PG8_LAS u32x4*)(st + bj * 64);
;                 float v[8];
; #pragma unroll
;                 for (int i = 0; i < 4; ++i) { v[2 * i] = __uint_as_float(xo[i] << 16) + acc[ai][bj][m][i >> 1][(2 * i) & 3]; v[2 * i + 1] = __uint_as_float(xo[i] & 0xffff0000u) + acc[ai][bj][m][i >> 1][(2 * i + 1) & 3]; }
;                 u32x4 w; w.x = cvt_pk_bf16(v[0], v[1]); w.y = cvt_pk_bf16(v[2], v[3]); w.z = cvt_pk_bf16(v[4], v[5]); w.w = cvt_pk_bf16(v[6], v[7]);
;                 *(PG8_LAS u32x4*)(st + bj * 64) = w;
;                 ss += ((v[0] * v[0] + v[1] * v[1]) + (v[2] * v[2] + v[3] * v[3])) + ((v[4] * v[4] + v[5] * v[5]) + (v[6] * v[6] + v[7] * v[7]));
;             }
; #pragma unroll
;             for (int i = 0; i < 2; ++i) { const int c = lane + 64 * i; const u32x4 w = *(const PG8_LAS u32x4*)(stg + (c >> 3) * 144 + (c & 7) * 16);
;                 *(u32x4*)(xo_ + (size_t)(row - fr + (c >> 3)) * 1024 + colw + (c & 7) * 8) = w; }
;             ss = sum_x16(ss); ss = sum_x32(ss);
	v_lshlrev_b32_e32 v110, 16, v106
	v_and_b32_e32 v106, 0xffff0000, v106
	v_add_f32_e32 v63, v63, v106
	v_lshlrev_b32_e32 v106, 16, v107
	v_add_f32_e32 v64, v64, v106
	v_and_b32_e32 v106, 0xffff0000, v107
	v_add_f32_e32 v65, v65, v106
	v_lshlrev_b32_e32 v106, 16, v108
	v_add_f32_e32 v106, v58, v106
	v_and_b32_e32 v58, 0xffff0000, v108
	v_add_f32_e32 v107, v59, v58
	v_lshlrev_b32_e32 v58, 16, v109
	v_add_f32_e32 v108, v60, v58
	v_and_b32_e32 v58, 0xffff0000, v109
	v_add_f32_e32 v62, v62, v110
	v_add_f32_e32 v109, v61, v58
	v_cvt_pk_bf16_f32 v58, v62, v63
	v_cvt_pk_bf16_f32 v59, v64, v65
	v_cvt_pk_bf16_f32 v60, v106, v107
	v_cvt_pk_bf16_f32 v61, v108, v109
	ds_write_b128 v210, v[58:61]
	v_mul_f32_e32 v58, v63, v63
	v_mul_f32_e32 v59, v65, v65
	v_fmac_f32_e32 v58, v62, v62
	v_fmac_f32_e32 v59, v64, v64
	v_add_f32_e32 v58, v58, v59
	v_mul_f32_e32 v59, v107, v107
	v_mul_f32_e32 v60, v109, v109
	v_fmac_f32_e32 v59, v106, v106
	v_fmac_f32_e32 v60, v108, v108
	v_add_f32_e32 v59, v59, v60
	v_add_f32_e32 v62, v58, v59
	ds_read_b128 v[58:61], v210 offset:64
	s_waitcnt lgkmcnt(0)
	v_lshlrev_b32_e32 v63, 16, v58
	v_and_b32_e32 v58, 0xffff0000, v58
	v_add_f32_e32 v55, v55, v58
	v_lshlrev_b32_e32 v58, 16, v59
	v_add_f32_e32 v56, v56, v58
	v_and_b32_e32 v58, 0xffff0000, v59
	v_add_f32_e32 v57, v57, v58
	v_lshlrev_b32_e32 v58, 16, v60
	v_add_f32_e32 v58, v50, v58
	v_and_b32_e32 v50, 0xffff0000, v60
	v_add_f32_e32 v59, v51, v50
	v_lshlrev_b32_e32 v50, 16, v61
	v_add_f32_e32 v60, v52, v50
	v_and_b32_e32 v50, 0xffff0000, v61
	v_add_f32_e32 v54, v54, v63
	v_add_f32_e32 v61, v53, v50
	v_cvt_pk_bf16_f32 v50, v54, v55
	v_cvt_pk_bf16_f32 v51, v56, v57
	v_cvt_pk_bf16_f32 v52, v58, v59
	v_cvt_pk_bf16_f32 v53, v60, v61
	ds_write_b128 v210, v[50:53] offset:64
	v_mul_f32_e32 v50, v55, v55
	v_mul_f32_e32 v51, v57, v57
	v_fmac_f32_e32 v50, v54, v54
	v_fmac_f32_e32 v51, v56, v56
	v_add_f32_e32 v50, v50, v51
	v_mul_f32_e32 v51, v59, v59
	v_mul_f32_e32 v52, v61, v61
	v_fmac_f32_e32 v51, v58, v58
	v_fmac_f32_e32 v52, v60, v60
	v_add_f32_e32 v51, v51, v52
	v_add_f32_e32 v50, v50, v51
	v_add_f32_e32 v56, v62, v50
	ds_read_b128 v[50:53], v211
	v_lshl_add_u64 v[54:55], s[76:77], 0, v[104:105]
	v_lshl_add_u64 v[54:55], v[54:55], 0, s[46:47]
	v_lshl_add_u64 v[54:55], v[54:55], 0, v[0:1]
	s_waitcnt lgkmcnt(0)
	global_store_dwordx4 v[54:55], v[50:53], off nt
	ds_read_b128 v[50:53], v211 offset:1152
	v_lshl_add_u64 v[54:55], s[76:77], 0, v[102:103]
	v_lshl_add_u64 v[54:55], v[54:55], 0, s[46:47]
	v_lshl_add_u64 v[54:55], v[54:55], 0, v[0:1]
	s_waitcnt lgkmcnt(0)
	global_store_dwordx4 v[54:55], v[50:53], off nt
	s_nop 1
	v_mov_b32_e32 v50, v56
	s_nop 1
	v_permlane16_swap_b32_e32 v56, v50
	v_add_f32_e32 v50, v56, v50
	v_mov_b32_e32 v51, v50
	s_nop 1
	v_permlane32_swap_b32_e32 v50, v51
	v_add_f32_e32 v164, v50, v51
	s_waitcnt vmcnt(7)
	ds_write_b128 v209, v[82:85]
	s_waitcnt vmcnt(6)
	ds_write_b128 v209, v[86:89] offset:1152
	ds_read_b128 v[50:53], v210
	s_waitcnt lgkmcnt(0)
	v_lshlrev_b32_e32 v54, 16, v50
	v_and_b32_e32 v50, 0xffff0000, v50
	v_add_f32_e32 v47, v47, v50
	v_and_b32_e32 v50, 0xffff0000, v51
	v_add_f32_e32 v49, v49, v50
	v_lshlrev_b32_e32 v50, 16, v52
	v_add_f32_e32 v50, v42, v50
	v_and_b32_e32 v42, 0xffff0000, v52
	v_lshlrev_b32_e32 v55, 16, v51
	v_add_f32_e32 v51, v43, v42
	v_lshlrev_b32_e32 v42, 16, v53
	v_add_f32_e32 v52, v44, v42
	v_and_b32_e32 v42, 0xffff0000, v53
	v_add_f32_e32 v46, v46, v54
	v_add_f32_e32 v48, v48, v55
	v_add_f32_e32 v53, v45, v42
	v_cvt_pk_bf16_f32 v42, v46, v47
	v_cvt_pk_bf16_f32 v43, v48, v49
	v_cvt_pk_bf16_f32 v44, v50, v51
	v_cvt_pk_bf16_f32 v45, v52, v53
	ds_write_b128 v210, v[42:45]
	v_mul_f32_e32 v42, v47, v47
	v_mul_f32_e32 v43, v49, v49
	v_fmac_f32_e32 v42, v46, v46
	v_fmac_f32_e32 v43, v48, v48
	v_add_f32_e32 v46, v42, v43
	ds_read_b128 v[42:45], v210 offset:64
	v_mul_f32_e32 v47, v51, v51
	v_mul_f32_e32 v48, v53, v53
	v_fmac_f32_e32 v47, v50, v50
	v_fmac_f32_e32 v48, v52, v52
	v_add_f32_e32 v47, v47, v48
	v_add_f32_e32 v46, v46, v47
	s_waitcnt lgkmcnt(0)
	v_lshlrev_b32_e32 v47, 16, v42
	v_and_b32_e32 v42, 0xffff0000, v42
	v_add_f32_e32 v39, v39, v42
	v_lshlrev_b32_e32 v42, 16, v43
	v_add_f32_e32 v40, v40, v42
	v_and_b32_e32 v42, 0xffff0000, v43
	v_add_f32_e32 v41, v41, v42
	v_lshlrev_b32_e32 v42, 16, v44
	v_add_f32_e32 v42, v34, v42
	v_and_b32_e32 v34, 0xffff0000, v44
	v_add_f32_e32 v43, v35, v34
	v_lshlrev_b32_e32 v34, 16, v45
	v_add_f32_e32 v44, v36, v34
	v_and_b32_e32 v34, 0xffff0000, v45
	v_add_f32_e32 v38, v38, v47
	v_add_f32_e32 v45, v37, v34
	v_cvt_pk_bf16_f32 v34, v38, v39
	v_cvt_pk_bf16_f32 v35, v40, v41
	v_cvt_pk_bf16_f32 v36, v42, v43
	v_cvt_pk_bf16_f32 v37, v44, v45
	ds_write_b128 v210, v[34:37] offset:64
	v_mul_f32_e32 v34, v39, v39
	v_mul_f32_e32 v35, v41, v41
	v_fmac_f32_e32 v34, v38, v38
	v_fmac_f32_e32 v35, v40, v40
	v_add_f32_e32 v34, v34, v35
	v_mul_f32_e32 v35, v43, v43
	v_mul_f32_e32 v36, v45, v45
	v_fmac_f32_e32 v35, v42, v42
	v_fmac_f32_e32 v36, v44, v44
	v_add_f32_e32 v35, v35, v36
	v_add_f32_e32 v34, v34, v35
	v_add_f32_e32 v44, v46, v34
	ds_read_b128 v[34:37], v211
	v_lshl_add_u64 v[38:39], s[76:77], 0, v[100:101]
	v_lshl_add_u64 v[38:39], v[38:39], 0, s[46:47]
	v_lshl_add_u64 v[42:43], v[38:39], 0, v[0:1]
	ds_read_b128 v[38:41], v211 offset:1152
	s_waitcnt lgkmcnt(1)
	global_store_dwordx4 v[42:43], v[34:37], off nt
	s_nop 1
	v_lshl_add_u64 v[34:35], s[76:77], 0, v[98:99]
	v_lshl_add_u64 v[34:35], v[34:35], 0, s[46:47]
	v_lshl_add_u64 v[34:35], v[34:35], 0, v[0:1]
	s_waitcnt lgkmcnt(0)
; #define PG8_LAS __attribute__((address_space(3)))
; __device__ __forceinline__ unsigned cvt_pk_bf16(float lo, float hi) { unsigned r; asm volatile("v_cvt_pk_bf16_f32 %0, %1, %2" : "=v"(r) : "v"(lo), "v"(hi)); return r; }
; __device__ __forceinline__ float sum_x16(float s) { auto r = __builtin_amdgcn_permlane16_swap(__float_as_uint(s), __float_as_uint(s), false, false); return __uint_as_float(r[0]) + __uint_as_float(r[1]); }
; __device__ __forceinline__ float sum_x32(float s) { auto r = __builtin_amdgcn_permlane32_swap(__float_as_uint(s), __float_as_uint(s), false, false); return __uint_as_float(r[0]) + __uint_as_float(r[1]); }
;     __device__ __forceinline__ void operator()(const f32x4 (&acc)[2][2][4][2], const Unit& u, int wr, int wc, int fr, int fq, PG8_LAS unsigned char* stg) const {
;     ...
;         for (int m = 0; m < 4; ++m) {
;             const int row = rowb + ai * HALF + m * 16 + fr;
; #pragma unroll
;             for (int i = 0; i < 2; ++i) { const int c = lane + 64 * i; *(PG8_LAS u32x4*)(stg + (c >> 3) * 144 + (c & 7) * 16) = xin[m][i]; }
;             float ss = 0.f;
; #pragma unroll
;             for (int bj = 0; bj < 2; ++bj) {
;                 const u32x4 xo = *(const PG8_LAS u32x4*)(st + bj * 64);
;                 float v[8];
; #pragma unroll
;                 for (int i = 0; i < 4; ++i) { v[2 * i] = __uint_as_float(xo[i] << 16) + acc[ai][bj][m][i >> 1][(2 * i) & 3]; v[2 * i + 1] = __uint_as_float(xo[i] & 0xffff0000u) + acc[ai][bj][m][i >> 1][(2 * i + 1) & 3]; }
;                 u32x4 w; w.x = cvt_pk_bf16(v[0], v[1]); w.y = cvt_pk_bf16(v[2], v[3]); w.z = cvt_pk_bf16(v[4], v[5]); w.w = cvt_pk_bf16(v[6], v[7]);
;                 *(PG8_LAS u32x4*)(st + bj * 64) = w;
;                 ss += ((v[0] * v[0] + v[1] * v[1]) + (v[2] * v[2] + v[3] * v[3])) + ((v[4] * v[4] + v[5] * v[5]) + (v[6] * v[6] + v[7] * v[7]));
;             }
; #pragma unroll
;             for (int i = 0; i < 2; ++i) { const int c = lane + 64 * i; const u32x4 w = *(const PG8_LAS u32x4*)(stg + (c >> 3) * 144 + (c & 7) * 16);
;                 *(u32x4*)(xo_ + (size_t)(row - fr + (c >> 3)) * 1024 + colw + (c & 7) * 8) = w; }
;             ss = sum_x16(ss); ss = sum_x32(ss);
;             if (fq == 0) po_[(size_t)(u.pn * 4 + wc) * 65536 + row] = ss;
;         }
;         }
	global_store_dwordx4 v[34:35], v[38:41], off nt
	v_mov_b32_e32 v34, v44
	s_nop 1
	v_permlane16_swap_b32_e32 v44, v34
	v_add_f32_e32 v34, v44, v34
	v_mov_b32_e32 v35, v34
	s_nop 1
	v_permlane32_swap_b32_e32 v34, v35
	v_add_f32_e32 v165, v34, v35
	s_waitcnt vmcnt(7)
	ds_write_b128 v209, v[70:73]
	s_waitcnt vmcnt(6)
	ds_write_b128 v209, v[74:77] offset:1152
	ds_read_b128 v[34:37], v210
	s_waitcnt lgkmcnt(0)
	v_lshlrev_b32_e32 v38, 16, v34
	v_and_b32_e32 v34, 0xffff0000, v34
	v_add_f32_e32 v31, v31, v34
	v_and_b32_e32 v34, 0xffff0000, v35
	v_add_f32_e32 v33, v33, v34
	v_lshlrev_b32_e32 v34, 16, v36
	v_add_f32_e32 v34, v26, v34
	v_and_b32_e32 v26, 0xffff0000, v36
	v_lshlrev_b32_e32 v39, 16, v35
	v_add_f32_e32 v35, v27, v26
	v_lshlrev_b32_e32 v26, 16, v37
	v_add_f32_e32 v36, v28, v26
	v_and_b32_e32 v26, 0xffff0000, v37
	v_add_f32_e32 v30, v30, v38
	v_add_f32_e32 v32, v32, v39
	v_add_f32_e32 v37, v29, v26
	v_cvt_pk_bf16_f32 v26, v30, v31
	v_cvt_pk_bf16_f32 v27, v32, v33
	v_cvt_pk_bf16_f32 v28, v34, v35
	v_cvt_pk_bf16_f32 v29, v36, v37
	ds_write_b128 v210, v[26:29]
	v_mul_f32_e32 v26, v31, v31
	v_mul_f32_e32 v27, v33, v33
	v_fmac_f32_e32 v26, v30, v30
	v_fmac_f32_e32 v27, v32, v32
	v_add_f32_e32 v30, v26, v27
	ds_read_b128 v[26:29], v210 offset:64
	v_mul_f32_e32 v31, v35, v35
	v_mul_f32_e32 v32, v37, v37
	v_fmac_f32_e32 v31, v34, v34
	v_fmac_f32_e32 v32, v36, v36
	v_add_f32_e32 v31, v31, v32
	v_add_f32_e32 v30, v30, v31
	s_waitcnt lgkmcnt(0)
	v_lshlrev_b32_e32 v31, 16, v26
	v_and_b32_e32 v26, 0xffff0000, v26
	v_add_f32_e32 v23, v23, v26
	v_lshlrev_b32_e32 v26, 16, v27
	v_add_f32_e32 v24, v24, v26
	v_and_b32_e32 v26, 0xffff0000, v27
	v_add_f32_e32 v25, v25, v26
	v_lshlrev_b32_e32 v26, 16, v28
	v_add_f32_e32 v26, v18, v26
	v_and_b32_e32 v18, 0xffff0000, v28
	v_add_f32_e32 v27, v19, v18
	v_lshlrev_b32_e32 v18, 16, v29
	v_add_f32_e32 v28, v20, v18
	v_and_b32_e32 v18, 0xffff0000, v29
	v_add_f32_e32 v22, v22, v31
	v_add_f32_e32 v29, v21, v18
	v_cvt_pk_bf16_f32 v18, v22, v23
	v_cvt_pk_bf16_f32 v19, v24, v25
	v_cvt_pk_bf16_f32 v20, v26, v27
	v_cvt_pk_bf16_f32 v21, v28, v29
	ds_write_b128 v210, v[18:21] offset:64
	v_mul_f32_e32 v18, v23, v23
	v_mul_f32_e32 v19, v25, v25
	v_fmac_f32_e32 v18, v22, v22
	v_fmac_f32_e32 v19, v24, v24
	v_add_f32_e32 v18, v18, v19
	v_mul_f32_e32 v19, v27, v27
	v_mul_f32_e32 v20, v29, v29
	v_fmac_f32_e32 v19, v26, v26
	v_fmac_f32_e32 v20, v28, v28
	v_add_f32_e32 v19, v19, v20
	v_add_f32_e32 v18, v18, v19
	v_add_f32_e32 v28, v30, v18
	ds_read_b128 v[18:21], v211
	v_lshl_add_u64 v[22:23], s[76:77], 0, v[94:95]
	v_lshl_add_u64 v[22:23], v[22:23], 0, s[46:47]
	v_lshl_add_u64 v[26:27], v[22:23], 0, v[0:1]
	ds_read_b128 v[22:25], v211 offset:1152
	s_waitcnt lgkmcnt(1)
	global_store_dwordx4 v[26:27], v[18:21], off nt
	s_nop 1
	v_lshl_add_u64 v[18:19], s[76:77], 0, v[92:93]
	v_lshl_add_u64 v[18:19], v[18:19], 0, s[46:47]
	v_lshl_add_u64 v[18:19], v[18:19], 0, v[0:1]
	s_waitcnt lgkmcnt(0)
	global_store_dwordx4 v[18:19], v[22:25], off nt
	v_mov_b32_e32 v18, v28
	s_nop 1
	v_permlane16_swap_b32_e32 v28, v18
	v_add_f32_e32 v18, v28, v18
	v_mov_b32_e32 v19, v18
	s_nop 1
	v_permlane32_swap_b32_e32 v18, v19
	v_add_f32_e32 v166, v18, v19
	s_waitcnt vmcnt(7)
	ds_write_b128 v209, v[66:69]
	s_waitcnt vmcnt(6)
	ds_write_b128 v209, v[78:81] offset:1152
	ds_read_b128 v[18:21], v210
	s_waitcnt lgkmcnt(0)
	v_lshlrev_b32_e32 v22, 16, v18
	v_and_b32_e32 v18, 0xffff0000, v18
	v_add_f32_e32 v15, v15, v18
	v_and_b32_e32 v18, 0xffff0000, v19
	v_add_f32_e32 v17, v17, v18
	v_lshlrev_b32_e32 v18, 16, v20
	v_add_f32_e32 v18, v10, v18
	v_and_b32_e32 v10, 0xffff0000, v20
	v_lshlrev_b32_e32 v23, 16, v19
	v_add_f32_e32 v19, v11, v10
	v_lshlrev_b32_e32 v10, 16, v21
	v_add_f32_e32 v20, v12, v10
	v_and_b32_e32 v10, 0xffff0000, v21
	v_add_f32_e32 v14, v14, v22
	v_add_f32_e32 v16, v16, v23
	v_add_f32_e32 v21, v13, v10
	v_cvt_pk_bf16_f32 v10, v14, v15
	v_cvt_pk_bf16_f32 v11, v16, v17
	v_cvt_pk_bf16_f32 v12, v18, v19
	v_cvt_pk_bf16_f32 v13, v20, v21
	ds_write_b128 v210, v[10:13]
	v_mul_f32_e32 v10, v15, v15
	v_mul_f32_e32 v11, v17, v17
	v_fmac_f32_e32 v10, v14, v14
	v_fmac_f32_e32 v11, v16, v16
	v_add_f32_e32 v14, v10, v11
	ds_read_b128 v[10:13], v210 offset:64
	v_mul_f32_e32 v15, v19, v19
	v_mul_f32_e32 v16, v21, v21
	v_fmac_f32_e32 v15, v18, v18
	v_fmac_f32_e32 v16, v20, v20
	v_add_f32_e32 v15, v15, v16
	v_add_f32_e32 v14, v14, v15
	s_waitcnt lgkmcnt(0)
	v_lshlrev_b32_e32 v15, 16, v10
	v_and_b32_e32 v10, 0xffff0000, v10
	v_add_f32_e32 v7, v7, v10
	v_lshlrev_b32_e32 v10, 16, v11
	v_add_f32_e32 v8, v8, v10
	v_and_b32_e32 v10, 0xffff0000, v11
	v_add_f32_e32 v9, v9, v10
	v_lshlrev_b32_e32 v10, 16, v12
	v_add_f32_e32 v10, v2, v10
	v_and_b32_e32 v2, 0xffff0000, v12
	v_add_f32_e32 v11, v3, v2
	v_lshlrev_b32_e32 v2, 16, v13
	v_add_f32_e32 v12, v4, v2
	v_and_b32_e32 v2, 0xffff0000, v13
	v_add_f32_e32 v6, v6, v15
	v_add_f32_e32 v13, v5, v2
	v_cvt_pk_bf16_f32 v2, v6, v7
	v_cvt_pk_bf16_f32 v3, v8, v9
	v_cvt_pk_bf16_f32 v4, v10, v11
	v_cvt_pk_bf16_f32 v5, v12, v13
	ds_write_b128 v210, v[2:5] offset:64
	v_mul_f32_e32 v2, v7, v7
	v_mul_f32_e32 v3, v9, v9
	v_fmac_f32_e32 v2, v6, v6
	v_fmac_f32_e32 v3, v8, v8
	v_add_f32_e32 v2, v2, v3
	v_mul_f32_e32 v3, v11, v11
	v_mul_f32_e32 v4, v13, v13
	v_fmac_f32_e32 v3, v10, v10
	v_fmac_f32_e32 v4, v12, v12
	v_add_f32_e32 v3, v3, v4
	v_add_f32_e32 v2, v2, v3
	v_add_f32_e32 v12, v14, v2
	ds_read_b128 v[2:5], v211
	v_lshl_add_u64 v[6:7], s[76:77], 0, v[90:91]
	v_lshl_add_u64 v[6:7], v[6:7], 0, s[46:47]
	v_lshl_add_u64 v[10:11], v[6:7], 0, v[0:1]
	ds_read_b128 v[6:9], v211 offset:1152
	s_waitcnt lgkmcnt(1)
	global_store_dwordx4 v[10:11], v[2:5], off nt
	s_nop 1
	v_lshl_add_u64 v[2:3], s[76:77], 0, v[96:97]
	v_lshl_add_u64 v[2:3], v[2:3], 0, s[46:47]
	v_lshl_add_u64 v[2:3], v[2:3], 0, v[0:1]
	s_waitcnt lgkmcnt(0)
	global_store_dwordx4 v[2:3], v[6:9], off nt
	v_mov_b32_e32 v2, v12
	s_nop 1
	v_permlane16_swap_b32_e32 v12, v2
	v_add_f32_e32 v2, v12, v2
	v_mov_b32_e32 v3, v2
	s_nop 1
	v_permlane32_swap_b32_e32 v2, v3
	v_add_f32_e32 v167, v2, v3
	v_mbcnt_lo_u32_b32 v200, -1, 0
	v_mbcnt_hi_u32_b32 v200, -1, v200
	v_lshrrev_b32_e32 v201, 4, v200
	v_cmp_eq_u32_e64 s[100:101], 1, v201
	s_nop 1
	v_cndmask_b32_e64 v212, v164, v165, s[100:101]
	v_cmp_eq_u32_e64 s[100:101], 2, v201
	s_nop 1
	v_cndmask_b32_e64 v212, v212, v166, s[100:101]
	v_cmp_eq_u32_e64 s[100:101], 3, v201
	s_nop 1
	v_cndmask_b32_e64 v212, v212, v167, s[100:101]
	s_nop 1
	s_add_u32 s100, s82, s44
	s_addc_u32 s101, s83, s45
	v_or_b32_e32 v201, s42, v174
	v_lshlrev_b32_e32 v201, 2, v201
	v_and_b32_e32 v200, 48, v200
	v_lshl_add_u32 v201, v200, 2, v201
	global_store_dword v201, v212, s[100:101] offset:512
	s_andn2_b64 vcc, exec, s[36:37]
	s_mov_b64 s[36:37], -1
	s_cbranch_vccnz .LBB0_915
	s_andn2_b64 vcc, exec, s[18:19]
	s_cbranch_vccnz .LBB0_914
	s_barrier
	s_branch .LBB0_914
